# GEMM k-loops: LDS-DMA issue order grouped (4 A-tile loads then 4 B-tile loads)
# speedup vs baseline: 1.0251x; 1.0251x over previous
.LBB0_231:
	s_add_i32 s47, s48, 0x8000
	s_and_b32 s27, s48, 0x8000
	s_and_b32 s50, s47, 0x8000
	s_add_i32 s48, s27, 0
	s_add_i32 s27, s50, 0
	s_add_u32 s70, s27, s71
	s_mov_b32 m0, s70
	s_waitcnt vmcnt(0) lgkmcnt(0)
	s_barrier
	global_load_lds_dwordx4 v244, s[96:97]
	s_add_u32 m0, s70, 0x1000
	s_nop 0
	global_load_lds_dwordx4 v246, s[96:97]
	s_add_u32 m0, s70, 0x2000
	s_nop 0
	global_load_lds_dwordx4 v248, s[96:97]
	s_add_u32 m0, s70, 0x3000
	s_nop 0
	global_load_lds_dwordx4 v250, s[96:97]
	s_add_u32 m0, s70, 0x4000
	s_nop 0
	global_load_lds_dwordx4 v245, s[72:73]
	s_add_u32 m0, s70, 0x5000
	s_nop 0
	global_load_lds_dwordx4 v247, s[72:73]
	s_add_u32 m0, s70, 0x6000
	s_nop 0
	global_load_lds_dwordx4 v249, s[72:73]
	s_add_u32 m0, s70, 0x7000
	s_nop 0
	global_load_lds_dwordx4 v251, s[72:73]
	s_add_u32 s96, s96, 0x80
	s_addc_u32 s97, s97, 0
	s_add_u32 s72, s72, 0x80
	s_addc_u32 s73, s73, 0
	v_add3_u32 v145, s48, v86, v87
	v_add3_u32 v208, s48, v87, v88
	v_add3_u32 v209, s48, v86, v89
	v_add3_u32 v210, s48, v88, v89
	ds_read_b128 v[104:107], v208
	ds_read_b128 v[100:103], v145 offset:16384
	ds_read_b128 v[108:111], v145 offset:18432
	ds_read_b128 v[164:167], v208 offset:2048
	ds_read_b128 v[112:115], v145 offset:20480
	ds_read_b128 v[116:119], v145 offset:22528
	ds_read_b128 v[120:123], v145 offset:24576
	ds_read_b128 v[124:127], v145 offset:26624
	ds_read_b128 v[128:131], v145 offset:28672
	ds_read_b128 v[132:135], v145 offset:30720
	ds_read_b128 v[200:203], v210
	ds_read_b128 v[168:171], v209 offset:16384
	ds_read_b128 v[172:175], v209 offset:18432
	ds_read_b128 v[204:207], v210 offset:2048
	ds_read_b128 v[176:179], v209 offset:20480
	ds_read_b128 v[180:183], v209 offset:22528
	ds_read_b128 v[184:187], v209 offset:24576
	ds_read_b128 v[188:191], v209 offset:26624
	ds_read_b128 v[192:195], v209 offset:28672
	ds_read_b128 v[196:199], v209 offset:30720
	s_add_u32 s24, s24, 0x80
	s_addc_u32 s25, s25, 0
	s_cmpk_eq_i32 s24, 0x780
	s_mov_b32 s48, s47
	s_waitcnt lgkmcnt(15)
	v_mfma_f32_16x16x32_bf16 v[60:63], v[100:103], v[104:107], v[60:63]
	v_mfma_f32_16x16x32_bf16 v[56:59], v[108:111], v[104:107], v[56:59]
	v_mfma_f32_16x16x32_bf16 v[24:27], v[100:103], v[164:167], v[24:27]
	v_mfma_f32_16x16x32_bf16 v[20:23], v[108:111], v[164:167], v[20:23]
	v_mfma_f32_16x16x32_bf16 v[52:55], v[112:115], v[104:107], v[52:55]
	v_mfma_f32_16x16x32_bf16 v[16:19], v[112:115], v[164:167], v[16:19]
	s_waitcnt lgkmcnt(14)
	v_mfma_f32_16x16x32_bf16 v[48:51], v[116:119], v[104:107], v[48:51]
	v_mfma_f32_16x16x32_bf16 v[12:15], v[116:119], v[164:167], v[12:15]
	s_waitcnt lgkmcnt(13)
	v_mfma_f32_16x16x32_bf16 v[44:47], v[120:123], v[104:107], v[44:47]
	v_mfma_f32_16x16x32_bf16 v[8:11], v[120:123], v[164:167], v[8:11]
	s_waitcnt lgkmcnt(12)
	v_mfma_f32_16x16x32_bf16 v[40:43], v[124:127], v[104:107], v[40:43]
	v_mfma_f32_16x16x32_bf16 v[4:7], v[124:127], v[164:167], v[4:7]
	s_waitcnt lgkmcnt(11)
	v_mfma_f32_16x16x32_bf16 v[36:39], v[128:131], v[104:107], v[36:39]
	v_mfma_f32_16x16x32_bf16 v[0:3], v[128:131], v[164:167], v[0:3]
	s_waitcnt lgkmcnt(10)
	v_mfma_f32_16x16x32_bf16 v[32:35], v[132:135], v[104:107], v[32:35]
	v_mfma_f32_16x16x32_bf16 v[28:31], v[132:135], v[164:167], v[28:31]
	s_waitcnt lgkmcnt(8)
	v_mfma_f32_16x16x32_bf16 v[60:63], v[168:171], v[200:203], v[60:63]
	s_waitcnt lgkmcnt(7)
	v_mfma_f32_16x16x32_bf16 v[56:59], v[172:175], v[200:203], v[56:59]
	s_waitcnt lgkmcnt(6)
	v_mfma_f32_16x16x32_bf16 v[24:27], v[168:171], v[204:207], v[24:27]
	v_mfma_f32_16x16x32_bf16 v[20:23], v[172:175], v[204:207], v[20:23]
	s_waitcnt lgkmcnt(5)
	v_mfma_f32_16x16x32_bf16 v[52:55], v[176:179], v[200:203], v[52:55]
	v_mfma_f32_16x16x32_bf16 v[16:19], v[176:179], v[204:207], v[16:19]
	s_waitcnt lgkmcnt(4)
	v_mfma_f32_16x16x32_bf16 v[48:51], v[180:183], v[200:203], v[48:51]
	v_mfma_f32_16x16x32_bf16 v[12:15], v[180:183], v[204:207], v[12:15]
	s_waitcnt lgkmcnt(3)
	v_mfma_f32_16x16x32_bf16 v[44:47], v[184:187], v[200:203], v[44:47]
	v_mfma_f32_16x16x32_bf16 v[8:11], v[184:187], v[204:207], v[8:11]
	s_waitcnt lgkmcnt(2)
	v_mfma_f32_16x16x32_bf16 v[40:43], v[188:191], v[200:203], v[40:43]
	v_mfma_f32_16x16x32_bf16 v[4:7], v[188:191], v[204:207], v[4:7]
	s_waitcnt lgkmcnt(1)
	v_mfma_f32_16x16x32_bf16 v[36:39], v[192:195], v[200:203], v[36:39]
	v_mfma_f32_16x16x32_bf16 v[0:3], v[192:195], v[204:207], v[0:3]
	s_waitcnt lgkmcnt(0)
	v_mfma_f32_16x16x32_bf16 v[32:35], v[196:199], v[200:203], v[32:35]
	v_mfma_f32_16x16x32_bf16 v[28:31], v[196:199], v[204:207], v[28:31]
	s_cbranch_scc0 .LBB0_231
	v_add_u32_e32 v64, s27, v86
	v_add_u32_e32 v136, v64, v87
	v_add3_u32 v108, s27, v87, v88
	s_waitcnt vmcnt(0)
	s_barrier
	ds_read_b128 v[80:83], v136 offset:16384
	ds_read_b128 v[100:103], v136 offset:18432
	ds_read_b128 v[104:107], v108
	ds_read_b128 v[108:111], v108 offset:2048
	ds_read_b128 v[112:115], v136 offset:20480
	ds_read_b128 v[116:119], v136 offset:22528
	ds_read_b128 v[128:131], v136 offset:28672
	s_waitcnt lgkmcnt(2)
	v_mfma_f32_16x16x32_bf16 v[120:123], v[112:115], v[104:107], v[52:55]
	s_nop 2
	ds_read_b128 v[52:55], v136 offset:24576
	ds_read_b128 v[124:127], v136 offset:26624
	s_cmp_gt_i32 s26, 11
	s_waitcnt lgkmcnt(0)
	v_mfma_f32_16x16x32_bf16 v[132:135], v[124:127], v[104:107], v[40:43]
	s_nop 2
	ds_read_b128 v[40:43], v136 offset:30720
	s_cselect_b64 s[24:25], -1, 0
	s_cmp_lt_i32 s26, 12
	v_mfma_f32_16x16x32_bf16 v[60:63], v[80:83], v[104:107], v[60:63]
	s_cselect_b64 s[48:49], -1, 0
	v_mfma_f32_16x16x32_bf16 v[56:59], v[100:103], v[104:107], v[56:59]
	v_mfma_f32_16x16x32_bf16 v[48:51], v[116:119], v[104:107], v[48:51]
	v_mfma_f32_16x16x32_bf16 v[44:47], v[52:55], v[104:107], v[44:47]
	v_mfma_f32_16x16x32_bf16 v[136:139], v[128:131], v[104:107], v[36:39]
	s_waitcnt lgkmcnt(0)
	v_mfma_f32_16x16x32_bf16 v[32:35], v[40:43], v[104:107], v[32:35]
	v_mfma_f32_16x16x32_bf16 v[104:107], v[52:55], v[108:111], v[8:11]
	s_nop 2
	v_add_u32_e32 v8, v64, v89
	v_mfma_f32_16x16x32_bf16 v[24:27], v[80:83], v[108:111], v[24:27]
	v_add3_u32 v9, s27, v89, v88
	v_lshl_or_b32 v64, s26, 7, v90
	s_sub_i32 s26, s26, 18
	v_mfma_f32_16x16x32_bf16 v[80:83], v[112:115], v[108:111], v[16:19]
	s_cmp_lt_u32 s26, 8
	s_cselect_b64 s[26:27], -1, 0
	s_or_b64 s[48:49], s[48:49], s[26:27]
	v_mfma_f32_16x16x32_bf16 v[112:115], v[124:127], v[108:111], v[4:7]
	s_mov_b64 s[26:27], -1
	s_andn2_b64 vcc, exec, s[48:49]
	s_nop 0
	ds_read_b128 v[4:7], v8 offset:16384
	v_mfma_f32_16x16x32_bf16 v[20:23], v[100:103], v[108:111], v[20:23]
	v_mfma_f32_16x16x32_bf16 v[100:103], v[116:119], v[108:111], v[12:15]
	v_mfma_f32_16x16x32_bf16 v[116:119], v[128:131], v[108:111], v[0:3]
	ds_read_b128 v[124:127], v8 offset:18432
	s_nop 1
	ds_read_b128 v[0:3], v9
	ds_read_b128 v[128:131], v9 offset:2048
	ds_read_b128 v[140:143], v8 offset:22528
	ds_read_b128 v[146:149], v8 offset:28672
	s_waitcnt lgkmcnt(3)
	v_mfma_f32_16x16x32_bf16 v[52:55], v[4:7], v[0:3], v[60:63]
	s_nop 2
	ds_read_b128 v[60:63], v8 offset:20480
	v_mfma_f32_16x16x32_bf16 v[108:111], v[40:43], v[108:111], v[28:31]
	s_waitcnt lgkmcnt(0)
	v_mfma_f32_16x16x32_bf16 v[36:39], v[60:63], v[0:3], v[120:123]
	s_nop 2
	ds_read_b128 v[120:123], v8 offset:24576
	v_mfma_f32_16x16x32_bf16 v[40:43], v[140:143], v[0:3], v[48:51]
	s_nop 2
	ds_read_b128 v[48:51], v8 offset:26624
	s_waitcnt lgkmcnt(0)
	v_mfma_f32_16x16x32_bf16 v[16:19], v[48:51], v[0:3], v[132:135]
	s_nop 2
	ds_read_b128 v[132:135], v8 offset:30720
	v_mfma_f32_16x16x32_bf16 v[56:59], v[124:127], v[0:3], v[56:59]
	v_mfma_f32_16x16x32_bf16 v[12:15], v[120:123], v[0:3], v[44:47]
	v_mfma_f32_16x16x32_bf16 v[8:11], v[146:149], v[0:3], v[136:139]
	s_waitcnt lgkmcnt(0)
	v_mfma_f32_16x16x32_bf16 v[0:3], v[132:135], v[0:3], v[32:35]
	v_mfma_f32_16x16x32_bf16 v[28:31], v[4:7], v[128:131], v[24:27]
	v_mfma_f32_16x16x32_bf16 v[20:23], v[124:127], v[128:131], v[20:23]
	v_mfma_f32_16x16x32_bf16 v[4:7], v[60:63], v[128:131], v[80:83]
	v_mfma_f32_16x16x32_bf16 v[24:27], v[140:143], v[128:131], v[100:103]
	s_nop 1
	v_lshl_add_u32 v80, s46, 7, v85
	v_mfma_f32_16x16x32_bf16 v[32:35], v[120:123], v[128:131], v[104:107]
	v_mfma_f32_16x16x32_bf16 v[44:47], v[48:51], v[128:131], v[112:115]
	v_mfma_f32_16x16x32_bf16 v[48:51], v[146:149], v[128:131], v[116:119]
	v_mfma_f32_16x16x32_bf16 v[60:63], v[132:135], v[128:131], v[108:111]
	s_cbranch_vccz .LBB0_240
	s_and_b32 s47, 0xffff, s45
	s_cmp_gt_u32 s47, 17
	s_cbranch_scc0 .LBB0_237
	s_cmp_eq_u32 s47, 26
	s_cselect_b64 s[26:27], -1, 0
	s_and_b64 s[48:49], s[10:11], s[26:27]
	s_and_saveexec_b64 s[26:27], s[48:49]
	s_cbranch_execz .LBB0_236
	global_load_dwordx4 v[100:103], v[72:73], off
	v_mad_i64_i32 v[82:83], s[48:49], v80, s28, v[70:71]
	v_or_b32_e32 v81, 16, v80
	s_waitcnt vmcnt(0)
	v_pk_add_f32 v[102:103], v[54:55], v[102:103]
	v_pk_add_f32 v[100:101], v[52:53], v[100:101]
	global_store_dwordx4 v[82:83], v[100:103], off
	global_load_dwordx4 v[100:103], v[72:73], off offset:16
	v_mad_i64_i32 v[82:83], s[48:49], v80, s28, v[74:75]
	s_waitcnt vmcnt(0)
	v_pk_add_f32 v[102:103], v[58:59], v[102:103]
	v_pk_add_f32 v[100:101], v[56:57], v[100:101]
	global_store_dwordx4 v[82:83], v[100:103], off
	global_load_dwordx4 v[100:103], v[72:73], off
	v_mad_i64_i32 v[82:83], s[48:49], v81, s28, v[70:71]
	s_waitcnt vmcnt(0)
	v_pk_add_f32 v[102:103], v[30:31], v[102:103]
	v_pk_add_f32 v[100:101], v[28:29], v[100:101]
	global_store_dwordx4 v[82:83], v[100:103], off
	global_load_dwordx4 v[100:103], v[72:73], off offset:16
	v_mad_i64_i32 v[82:83], s[48:49], v81, s28, v[74:75]
	s_waitcnt vmcnt(0)
	v_pk_add_f32 v[102:103], v[22:23], v[102:103]
	v_pk_add_f32 v[100:101], v[20:21], v[100:101]
	global_store_dwordx4 v[82:83], v[100:103], off

.LBB0_855:
	s_add_i32 s45, s43, 0x8000
	s_and_b32 s44, s45, 0x8000
	s_add_i32 s44, s44, 0
	s_add_u32 s86, s44, s87
	s_mov_b32 m0, s86
	s_waitcnt vmcnt(0) lgkmcnt(0)
	s_barrier
	global_load_lds_dwordx4 v244, s[96:97]
	s_add_u32 m0, s86, 0x1000
	s_nop 0
	global_load_lds_dwordx4 v246, s[96:97]
	s_add_u32 m0, s86, 0x2000
	s_nop 0
	global_load_lds_dwordx4 v248, s[96:97]
	s_add_u32 m0, s86, 0x3000
	s_nop 0
	global_load_lds_dwordx4 v250, s[96:97]
	s_add_u32 m0, s86, 0x4000
	s_nop 0
	global_load_lds_dwordx4 v245, s[88:89]
	s_add_u32 m0, s86, 0x5000
	s_nop 0
	global_load_lds_dwordx4 v247, s[88:89]
	s_add_u32 m0, s86, 0x6000
	s_nop 0
	global_load_lds_dwordx4 v249, s[88:89]
	s_add_u32 m0, s86, 0x7000
	s_nop 0
	global_load_lds_dwordx4 v251, s[88:89]
	s_add_u32 s96, s96, 0x80
	s_addc_u32 s97, s97, 0
	s_add_u32 s88, s88, 0x80
	s_addc_u32 s89, s89, 0
	s_and_b32 s43, s43, 0x8000
	s_add_i32 s43, s43, 0
	v_add3_u32 v212, s43, v88, v89
	v_add3_u32 v213, s43, v89, v90
	v_add3_u32 v214, s43, v88, v91
	v_add3_u32 v215, s43, v90, v91
	ds_read_b128 v[106:109], v213
	ds_read_b128 v[76:79], v212 offset:16384
	ds_read_b128 v[102:105], v212 offset:18432
	ds_read_b128 v[110:113], v213 offset:2048
	ds_read_b128 v[114:117], v212 offset:20480
	ds_read_b128 v[118:121], v212 offset:22528
	ds_read_b128 v[122:125], v212 offset:24576
	ds_read_b128 v[126:129], v212 offset:26624
	ds_read_b128 v[130:133], v212 offset:28672
	ds_read_b128 v[134:137], v212 offset:30720
	ds_read_b128 v[180:183], v215
	ds_read_b128 v[172:175], v214 offset:16384
	ds_read_b128 v[176:179], v214 offset:18432
	ds_read_b128 v[184:187], v215 offset:2048
	ds_read_b128 v[188:191], v214 offset:20480
	ds_read_b128 v[192:195], v214 offset:22528
	ds_read_b128 v[196:199], v214 offset:24576
	ds_read_b128 v[200:203], v214 offset:26624
	ds_read_b128 v[204:207], v214 offset:28672
	ds_read_b128 v[208:211], v214 offset:30720
	s_add_u32 s34, s34, 0x80
	s_addc_u32 s35, s35, 0
	s_cmpk_eq_i32 s34, 0x780
	s_mov_b32 s43, s45
	s_waitcnt lgkmcnt(15)
	v_mfma_f32_16x16x32_bf16 v[60:63], v[76:79], v[106:109], v[60:63]
	v_mfma_f32_16x16x32_bf16 v[56:59], v[102:105], v[106:109], v[56:59]
	v_mfma_f32_16x16x32_bf16 v[24:27], v[76:79], v[110:113], v[24:27]
	v_mfma_f32_16x16x32_bf16 v[20:23], v[102:105], v[110:113], v[20:23]
	v_mfma_f32_16x16x32_bf16 v[52:55], v[114:117], v[106:109], v[52:55]
	v_mfma_f32_16x16x32_bf16 v[16:19], v[114:117], v[110:113], v[16:19]
	s_waitcnt lgkmcnt(14)
	v_mfma_f32_16x16x32_bf16 v[48:51], v[118:121], v[106:109], v[48:51]
	v_mfma_f32_16x16x32_bf16 v[12:15], v[118:121], v[110:113], v[12:15]
	s_waitcnt lgkmcnt(13)
	v_mfma_f32_16x16x32_bf16 v[44:47], v[122:125], v[106:109], v[44:47]
	v_mfma_f32_16x16x32_bf16 v[8:11], v[122:125], v[110:113], v[8:11]
	s_waitcnt lgkmcnt(12)
	v_mfma_f32_16x16x32_bf16 v[40:43], v[126:129], v[106:109], v[40:43]
	v_mfma_f32_16x16x32_bf16 v[4:7], v[126:129], v[110:113], v[4:7]
	s_waitcnt lgkmcnt(11)
	v_mfma_f32_16x16x32_bf16 v[32:35], v[130:133], v[106:109], v[32:35]
	v_mfma_f32_16x16x32_bf16 v[0:3], v[130:133], v[110:113], v[0:3]
	s_waitcnt lgkmcnt(10)
	v_mfma_f32_16x16x32_bf16 v[28:31], v[134:137], v[106:109], v[28:31]
	v_mfma_f32_16x16x32_bf16 v[36:39], v[134:137], v[110:113], v[36:39]
	s_waitcnt lgkmcnt(8)
	v_mfma_f32_16x16x32_bf16 v[60:63], v[172:175], v[180:183], v[60:63]
	s_waitcnt lgkmcnt(7)
	v_mfma_f32_16x16x32_bf16 v[56:59], v[176:179], v[180:183], v[56:59]
	s_waitcnt lgkmcnt(6)
	v_mfma_f32_16x16x32_bf16 v[24:27], v[172:175], v[184:187], v[24:27]
	v_mfma_f32_16x16x32_bf16 v[20:23], v[176:179], v[184:187], v[20:23]
	s_waitcnt lgkmcnt(5)
	v_mfma_f32_16x16x32_bf16 v[52:55], v[188:191], v[180:183], v[52:55]
	v_mfma_f32_16x16x32_bf16 v[16:19], v[188:191], v[184:187], v[16:19]
	s_waitcnt lgkmcnt(4)
	v_mfma_f32_16x16x32_bf16 v[48:51], v[192:195], v[180:183], v[48:51]
	v_mfma_f32_16x16x32_bf16 v[12:15], v[192:195], v[184:187], v[12:15]
	s_waitcnt lgkmcnt(3)
	v_mfma_f32_16x16x32_bf16 v[44:47], v[196:199], v[180:183], v[44:47]
	v_mfma_f32_16x16x32_bf16 v[8:11], v[196:199], v[184:187], v[8:11]
	s_waitcnt lgkmcnt(2)
	v_mfma_f32_16x16x32_bf16 v[40:43], v[200:203], v[180:183], v[40:43]
	v_mfma_f32_16x16x32_bf16 v[4:7], v[200:203], v[184:187], v[4:7]
	s_waitcnt lgkmcnt(1)
	v_mfma_f32_16x16x32_bf16 v[32:35], v[204:207], v[180:183], v[32:35]
	v_mfma_f32_16x16x32_bf16 v[0:3], v[204:207], v[184:187], v[0:3]
	s_waitcnt lgkmcnt(0)
	v_mfma_f32_16x16x32_bf16 v[28:31], v[208:211], v[180:183], v[28:31]
	v_mfma_f32_16x16x32_bf16 v[36:39], v[208:211], v[184:187], v[36:39]
	s_cbranch_scc0 .LBB0_855
	v_add_u32_e32 v80, s44, v88
	v_add_u32_e32 v81, v80, v89
	v_add3_u32 v106, s44, v89, v90
	s_waitcnt vmcnt(0)
	s_barrier
	ds_read_b128 v[72:75], v81 offset:16384
	ds_read_b128 v[76:79], v81 offset:18432
	ds_read_b128 v[102:105], v106
	ds_read_b128 v[106:109], v106 offset:2048
	ds_read_b128 v[110:113], v81 offset:20480
	ds_read_b128 v[114:117], v81 offset:22528
	ds_read_b128 v[118:121], v81 offset:24576
	ds_read_b128 v[122:125], v81 offset:26624
	ds_read_b128 v[126:129], v81 offset:28672
	ds_read_b128 v[130:133], v81 offset:30720
	v_add_u32_e32 v80, v80, v91
	s_waitcnt lgkmcnt(7)
	v_mfma_f32_16x16x32_bf16 v[60:63], v[72:75], v[102:105], v[60:63]
	s_lshl_b32 s42, s42, 7
	v_mfma_f32_16x16x32_bf16 v[56:59], v[76:79], v[102:105], v[56:59]
	s_waitcnt lgkmcnt(4)
	v_mfma_f32_16x16x32_bf16 v[48:51], v[114:117], v[102:105], v[48:51]
	s_waitcnt lgkmcnt(3)
	v_mfma_f32_16x16x32_bf16 v[44:47], v[118:121], v[102:105], v[44:47]
	s_waitcnt lgkmcnt(2)
	v_mfma_f32_16x16x32_bf16 v[40:43], v[122:125], v[102:105], v[40:43]
	s_waitcnt lgkmcnt(1)
	v_mfma_f32_16x16x32_bf16 v[32:35], v[126:129], v[102:105], v[32:35]
	s_waitcnt lgkmcnt(0)
	v_mfma_f32_16x16x32_bf16 v[28:31], v[130:133], v[102:105], v[28:31]
	v_mfma_f32_16x16x32_bf16 v[24:27], v[72:75], v[106:109], v[24:27]
	ds_read_b128 v[72:75], v80 offset:16384
	v_mfma_f32_16x16x32_bf16 v[52:55], v[110:113], v[102:105], v[52:55]
	v_mfma_f32_16x16x32_bf16 v[20:23], v[76:79], v[106:109], v[20:23]
	v_mfma_f32_16x16x32_bf16 v[16:19], v[110:113], v[106:109], v[16:19]
	v_mfma_f32_16x16x32_bf16 v[12:15], v[114:117], v[106:109], v[12:15]
	v_mfma_f32_16x16x32_bf16 v[8:11], v[118:121], v[106:109], v[8:11]
	v_mfma_f32_16x16x32_bf16 v[4:7], v[122:125], v[106:109], v[4:7]
	v_mfma_f32_16x16x32_bf16 v[0:3], v[126:129], v[106:109], v[0:3]
	v_mfma_f32_16x16x32_bf16 v[102:105], v[130:133], v[106:109], v[36:39]
	s_nop 2
	v_add3_u32 v36, s44, v91, v90
	ds_read_b128 v[76:79], v80 offset:18432
	ds_read_b128 v[106:109], v36
	ds_read_b128 v[110:113], v36 offset:2048
	ds_read_b128 v[130:133], v80 offset:28672
	ds_read_b128 v[134:137], v80 offset:30720
	ds_read_b128 v[114:117], v80 offset:20480
	ds_read_b128 v[118:121], v80 offset:22528
	ds_read_b128 v[122:125], v80 offset:24576
	ds_read_b128 v[126:129], v80 offset:26624
	s_waitcnt lgkmcnt(7)
	v_mfma_f32_16x16x32_bf16 v[60:63], v[72:75], v[106:109], v[60:63]
	v_readlane_b32 s44, v252, 5
	v_readlane_b32 s48, v252, 9
	v_readlane_b32 s49, v252, 10
	s_waitcnt lgkmcnt(5)
	v_mfma_f32_16x16x32_bf16 v[36:39], v[130:133], v[106:109], v[32:35]
	v_readlane_b32 s45, v252, 6
	v_readlane_b32 s46, v252, 7
	v_readlane_b32 s47, v252, 8
	s_waitcnt lgkmcnt(4)
	v_mfma_f32_16x16x32_bf16 v[32:35], v[134:137], v[106:109], v[28:31]
	v_readlane_b32 s50, v252, 11
	v_readlane_b32 s51, v252, 12
	v_readlane_b32 s52, v252, 13
	v_mfma_f32_16x16x32_bf16 v[28:31], v[72:75], v[110:113], v[24:27]
	v_add_u32_e32 v72, s42, v82
	v_mul_hi_i32 v73, v72, s36
	v_lshrrev_b32_e32 v74, 31, v73
	v_mfma_f32_16x16x32_bf16 v[24:27], v[76:79], v[110:113], v[20:23]
	v_readlane_b32 s53, v252, 14
	v_readlane_b32 s54, v252, 15
	v_readlane_b32 s55, v252, 16
	s_waitcnt lgkmcnt(3)
	v_mfma_f32_16x16x32_bf16 v[20:23], v[114:117], v[110:113], v[16:19]
	v_readlane_b32 s56, v252, 17
	v_readlane_b32 s57, v252, 18
	v_readlane_b32 s58, v252, 19
	s_waitcnt lgkmcnt(2)
	v_mfma_f32_16x16x32_bf16 v[16:19], v[118:121], v[110:113], v[12:15]
	v_readlane_b32 s59, v252, 20
	s_waitcnt lgkmcnt(1)
	v_mfma_f32_16x16x32_bf16 v[12:15], v[122:125], v[110:113], v[8:11]
	s_waitcnt lgkmcnt(0)
	v_mfma_f32_16x16x32_bf16 v[8:11], v[126:129], v[110:113], v[4:7]
	s_nop 2
	v_ashrrev_i32_e32 v4, 11, v73
	v_mfma_f32_16x16x32_bf16 v[56:59], v[76:79], v[106:109], v[56:59]
	v_add_u32_e32 v73, v4, v74
	v_mad_i32_i24 v75, v73, s37, v72
	v_lshlrev_b32_e32 v78, 13, v73
	v_mfma_f32_16x16x32_bf16 v[52:55], v[114:117], v[106:109], v[52:55]
	v_cmp_lt_i32_e32 vcc, s38, v75
	v_mov_b64_e32 v[76:77], s[48:49]
	v_add3_u32 v74, v78, v75, s39
	v_mfma_f32_16x16x32_bf16 v[48:51], v[118:121], v[106:109], v[48:51]
	v_mfma_f32_16x16x32_bf16 v[44:47], v[122:125], v[106:109], v[44:47]
	v_mfma_f32_16x16x32_bf16 v[40:43], v[126:129], v[106:109], v[40:43]
	v_mfma_f32_16x16x32_bf16 v[0:3], v[130:133], v[110:113], v[0:3]
	v_mfma_f32_16x16x32_bf16 v[4:7], v[134:137], v[110:113], v[102:105]
	s_and_saveexec_b64 s[34:35], vcc
	s_xor_b64 s[34:35], exec, s[34:35]
	s_cbranch_execz .LBB0_858
	v_readlane_b32 s44, v252, 5
	v_readlane_b32 s45, v252, 6
	v_add3_u32 v72, v78, v75, s39
	v_readlane_b32 s46, v252, 7
	v_readlane_b32 s47, v252, 8
	v_readlane_b32 s48, v252, 9
	v_readlane_b32 s49, v252, 10
	v_readlane_b32 s50, v252, 11
	v_readlane_b32 s51, v252, 12
	v_readlane_b32 s52, v252, 13
	v_readlane_b32 s53, v252, 14
	v_readlane_b32 s54, v252, 15
	v_readlane_b32 s55, v252, 16
	v_readlane_b32 s56, v252, 17
	v_readlane_b32 s57, v252, 18
	v_readlane_b32 s58, v252, 19
	v_readlane_b32 s59, v252, 20
	v_mov_b64_e32 v[76:77], s[44:45]
	s_or_saveexec_b64 s[34:35], s[34:35]
	v_lshl_add_u32 v102, v73, 8, v75
	s_xor_b64 exec, exec, s[34:35]
	s_branch .LBB0_859

.LBB0_1006:
	s_add_i32 s37, s35, 0x8000
	s_and_b32 s36, s37, 0x8000
	s_add_i32 s36, s36, 0
	s_add_u32 s86, s36, s87
	s_mov_b32 m0, s86
	s_waitcnt vmcnt(0) lgkmcnt(0)
	s_barrier
	global_load_lds_dwordx4 v244, s[96:97]
	s_add_u32 m0, s86, 0x1000
	s_nop 0
	global_load_lds_dwordx4 v246, s[96:97]
	s_add_u32 m0, s86, 0x2000
	s_nop 0
	global_load_lds_dwordx4 v248, s[96:97]
	s_add_u32 m0, s86, 0x3000
	s_nop 0
	global_load_lds_dwordx4 v250, s[96:97]
	s_add_u32 m0, s86, 0x4000
	s_nop 0
	global_load_lds_dwordx4 v245, s[88:89]
	s_add_u32 m0, s86, 0x5000
	s_nop 0
	global_load_lds_dwordx4 v247, s[88:89]
	s_add_u32 m0, s86, 0x6000
	s_nop 0
	global_load_lds_dwordx4 v249, s[88:89]
	s_add_u32 m0, s86, 0x7000
	s_nop 0
	global_load_lds_dwordx4 v251, s[88:89]
	s_add_u32 s96, s96, 0x80
	s_addc_u32 s97, s97, 0
	s_add_u32 s88, s88, 0x80
	s_addc_u32 s89, s89, 0
	s_and_b32 s35, s35, 0x8000
	s_add_i32 s35, s35, 0
	v_add3_u32 v143, s35, v80, v81
	v_add3_u32 v145, s35, v81, v82
	v_add3_u32 v206, s35, v80, v83
	v_add3_u32 v207, s35, v82, v83
	ds_read_b128 v[102:105], v145
	ds_read_b128 v[94:97], v143 offset:16384
	ds_read_b128 v[98:101], v143 offset:18432
	ds_read_b128 v[106:109], v145 offset:2048
	ds_read_b128 v[110:113], v143 offset:20480
	ds_read_b128 v[114:117], v143 offset:22528
	ds_read_b128 v[118:121], v143 offset:24576
	ds_read_b128 v[122:125], v143 offset:26624
	ds_read_b128 v[126:129], v143 offset:28672
	ds_read_b128 v[130:133], v143 offset:30720
	ds_read_b128 v[174:177], v207
	ds_read_b128 v[166:169], v206 offset:16384
	ds_read_b128 v[170:173], v206 offset:18432
	ds_read_b128 v[178:181], v207 offset:2048
	ds_read_b128 v[182:185], v206 offset:20480
	ds_read_b128 v[186:189], v206 offset:22528
	ds_read_b128 v[190:193], v206 offset:24576
	ds_read_b128 v[194:197], v206 offset:26624
	ds_read_b128 v[198:201], v206 offset:28672
	ds_read_b128 v[202:205], v206 offset:30720
	s_add_u32 s26, s26, 0x80
	s_addc_u32 s27, s27, 0
	s_cmpk_eq_i32 s26, 0x780
	s_mov_b32 s35, s37
	s_waitcnt lgkmcnt(15)
	v_mfma_f32_16x16x32_bf16 v[60:63], v[94:97], v[102:105], v[60:63]
	v_mfma_f32_16x16x32_bf16 v[56:59], v[98:101], v[102:105], v[56:59]
	v_mfma_f32_16x16x32_bf16 v[28:31], v[94:97], v[106:109], v[28:31]
	v_mfma_f32_16x16x32_bf16 v[24:27], v[98:101], v[106:109], v[24:27]
	v_mfma_f32_16x16x32_bf16 v[52:55], v[110:113], v[102:105], v[52:55]
	v_mfma_f32_16x16x32_bf16 v[16:19], v[110:113], v[106:109], v[16:19]
	s_waitcnt lgkmcnt(14)
	v_mfma_f32_16x16x32_bf16 v[48:51], v[114:117], v[102:105], v[48:51]
	v_mfma_f32_16x16x32_bf16 v[12:15], v[114:117], v[106:109], v[12:15]
	s_waitcnt lgkmcnt(13)
	v_mfma_f32_16x16x32_bf16 v[44:47], v[118:121], v[102:105], v[44:47]
	v_mfma_f32_16x16x32_bf16 v[8:11], v[118:121], v[106:109], v[8:11]
	s_waitcnt lgkmcnt(12)
	v_mfma_f32_16x16x32_bf16 v[40:43], v[122:125], v[102:105], v[40:43]
	v_mfma_f32_16x16x32_bf16 v[4:7], v[122:125], v[106:109], v[4:7]
	s_waitcnt lgkmcnt(11)
	v_mfma_f32_16x16x32_bf16 v[36:39], v[126:129], v[102:105], v[36:39]
	v_mfma_f32_16x16x32_bf16 v[0:3], v[126:129], v[106:109], v[0:3]
	s_waitcnt lgkmcnt(10)
	v_mfma_f32_16x16x32_bf16 v[32:35], v[130:133], v[102:105], v[32:35]
	v_mfma_f32_16x16x32_bf16 v[20:23], v[130:133], v[106:109], v[20:23]
	s_waitcnt lgkmcnt(8)
	v_mfma_f32_16x16x32_bf16 v[60:63], v[166:169], v[174:177], v[60:63]
	s_waitcnt lgkmcnt(7)
	v_mfma_f32_16x16x32_bf16 v[56:59], v[170:173], v[174:177], v[56:59]
	s_waitcnt lgkmcnt(6)
	v_mfma_f32_16x16x32_bf16 v[28:31], v[166:169], v[178:181], v[28:31]
	v_mfma_f32_16x16x32_bf16 v[24:27], v[170:173], v[178:181], v[24:27]
	s_waitcnt lgkmcnt(5)
	v_mfma_f32_16x16x32_bf16 v[52:55], v[182:185], v[174:177], v[52:55]
	v_mfma_f32_16x16x32_bf16 v[16:19], v[182:185], v[178:181], v[16:19]
	s_waitcnt lgkmcnt(4)
	v_mfma_f32_16x16x32_bf16 v[48:51], v[186:189], v[174:177], v[48:51]
	v_mfma_f32_16x16x32_bf16 v[12:15], v[186:189], v[178:181], v[12:15]
	s_waitcnt lgkmcnt(3)
	v_mfma_f32_16x16x32_bf16 v[44:47], v[190:193], v[174:177], v[44:47]
	v_mfma_f32_16x16x32_bf16 v[8:11], v[190:193], v[178:181], v[8:11]
	s_waitcnt lgkmcnt(2)
	v_mfma_f32_16x16x32_bf16 v[40:43], v[194:197], v[174:177], v[40:43]
	v_mfma_f32_16x16x32_bf16 v[4:7], v[194:197], v[178:181], v[4:7]
	s_waitcnt lgkmcnt(1)
	v_mfma_f32_16x16x32_bf16 v[36:39], v[198:201], v[174:177], v[36:39]
	v_mfma_f32_16x16x32_bf16 v[0:3], v[198:201], v[178:181], v[0:3]
	s_waitcnt lgkmcnt(0)
	v_mfma_f32_16x16x32_bf16 v[32:35], v[202:205], v[174:177], v[32:35]
	v_mfma_f32_16x16x32_bf16 v[20:23], v[202:205], v[178:181], v[20:23]
	s_cbranch_scc0 .LBB0_1006
	v_add_u32_e32 v138, s36, v80
	v_add_u32_e32 v126, v138, v81
	s_waitcnt vmcnt(0)
	s_barrier
	ds_read_b128 v[74:77], v126 offset:16384
	v_add3_u32 v102, s36, v81, v82
	ds_read_b128 v[94:97], v102
	ds_read_b128 v[98:101], v126 offset:18432
	ds_read_b128 v[102:105], v102 offset:2048
	ds_read_b128 v[106:109], v126 offset:20480
	ds_read_b128 v[110:113], v126 offset:22528
	ds_read_b128 v[114:117], v126 offset:24576
	ds_read_b128 v[118:121], v126 offset:26624
	v_add3_u32 v134, s36, v83, v82
	v_add_u32_e32 v142, v138, v83
	ds_read_b128 v[122:125], v126 offset:28672
	ds_read_b128 v[126:129], v126 offset:30720
	ds_read_b128 v[130:133], v134
	ds_read_b128 v[134:137], v134 offset:2048
	ds_read_b128 v[138:141], v142 offset:16384
	ds_read_b128 v[146:149], v142 offset:18432
	s_waitcnt lgkmcnt(11)
	v_mfma_f32_16x16x32_bf16 v[56:59], v[98:101], v[94:97], v[56:59]
	s_lshl_b32 s36, s34, 7
	s_lshl_b32 s26, s33, 7
	s_ashr_i32 s27, s26, 31
	v_mfma_f32_16x16x32_bf16 v[60:63], v[74:77], v[94:97], v[60:63]
	s_lshl_b64 s[26:27], s[26:27], 1
	s_add_i32 s31, s31, s28
	s_cmpk_gt_i32 s31, 0x107f
	s_waitcnt lgkmcnt(0)
	v_mfma_f32_16x16x32_bf16 v[56:59], v[146:149], v[130:133], v[56:59]
	v_mfma_f32_16x16x32_bf16 v[48:51], v[110:113], v[94:97], v[48:51]
	v_mfma_f32_16x16x32_bf16 v[52:55], v[106:109], v[94:97], v[52:55]
	s_nop 5
	v_max_f32_e32 v56, v56, v56
	v_max_f32_e32 v57, v57, v57
	v_max_f32_e32 v56, 0, v56
	v_mfma_f32_16x16x32_bf16 v[44:47], v[114:117], v[94:97], v[44:47]
	v_max_f32_e32 v57, 0, v57
	v_max_f32_e32 v59, v59, v59
	v_max_f32_e32 v59, 0, v59
	v_mfma_f32_16x16x32_bf16 v[40:43], v[118:121], v[94:97], v[40:43]
	v_mfma_f32_16x16x32_bf16 v[36:39], v[122:125], v[94:97], v[36:39]
	v_mfma_f32_16x16x32_bf16 v[32:35], v[126:129], v[94:97], v[32:35]
	ds_read_b128 v[94:97], v142 offset:20480
	ds_read_b128 v[150:153], v142 offset:22528
	ds_read_b128 v[154:157], v142 offset:24576
	ds_read_b128 v[158:161], v142 offset:26624
	v_mfma_f32_16x16x32_bf16 v[60:63], v[138:141], v[130:133], v[60:63]
	s_waitcnt lgkmcnt(2)
	v_mfma_f32_16x16x32_bf16 v[48:51], v[150:153], v[130:133], v[48:51]
	v_mfma_f32_16x16x32_bf16 v[16:19], v[106:109], v[102:105], v[16:19]
	v_mul_f32_e64 v106, v56, v56
	v_mul_f32_e64 v107, v57, v57
	v_max_f32_e32 v57, v58, v58
	s_nop 1
	v_max_f32_e32 v60, v60, v60
	v_mfma_f32_16x16x32_bf16 v[24:27], v[98:101], v[102:105], v[24:27]
	v_add_u32_e32 v100, s36, v79
	v_mov_b64_e32 v[98:99], s[0:1]
	v_max_f32_e32 v61, v61, v61
	v_max_f32_e32 v56, v62, v62
	v_max_f32_e32 v58, 0, v57
	v_max_f32_e32 v57, v63, v63
	v_mad_i64_i32 v[100:101], s[34:35], v100, s30, v[98:99]
	v_max_f32_e32 v60, 0, v60
	v_max_f32_e32 v61, 0, v61
	v_max_f32_e32 v56, 0, v56
	v_max_f32_e32 v57, 0, v57
	v_mfma_f32_16x16x32_bf16 v[52:55], v[94:97], v[130:133], v[52:55]
	v_lshl_add_u64 v[100:101], v[100:101], 0, s[26:27]
	v_pk_mul_f32 v[60:61], v[60:61], v[60:61]
	v_pk_mul_f32 v[62:63], v[56:57], v[56:57]
	v_mfma_f32_16x16x32_bf16 v[28:31], v[74:77], v[102:105], v[28:31]
	v_max_f32_e32 v48, v48, v48
	v_max_f32_e32 v49, v49, v49
	ds_read_b128 v[74:77], v142 offset:28672
	ds_read_b128 v[162:165], v142 offset:30720
	v_mfma_f32_16x16x32_bf16 v[12:15], v[110:113], v[102:105], v[12:15]
	v_lshl_add_u64 v[100:101], v[100:101], 0, v[64:65]
	v_cvt_pk_bf16_f32 v56, v60, v61
	v_cvt_pk_bf16_f32 v57, v62, v63
	v_mfma_f32_16x16x32_bf16 v[8:11], v[114:117], v[102:105], v[8:11]
	v_max_f32_e32 v48, 0, v48
	v_max_f32_e32 v49, 0, v49
	v_max_f32_e32 v52, v52, v52
	v_mfma_f32_16x16x32_bf16 v[4:7], v[118:121], v[102:105], v[4:7]
	v_max_f32_e32 v53, v53, v53
	v_max_f32_e32 v51, v51, v51
	v_max_f32_e32 v52, 0, v52
	v_mfma_f32_16x16x32_bf16 v[0:3], v[122:125], v[102:105], v[0:3]
	v_max_f32_e32 v53, 0, v53
	v_max_f32_e32 v51, 0, v51
	v_pk_mul_f32 v[52:53], v[52:53], v[52:53]
	v_mfma_f32_16x16x32_bf16 v[20:23], v[126:129], v[102:105], v[20:23]
	v_mul_f32_e64 v102, v58, v58
	v_mul_f32_e64 v103, v59, v59
	v_cvt_pk_bf16_f32 v58, v106, v107
	v_cvt_pk_bf16_f32 v59, v102, v103
	s_waitcnt lgkmcnt(2)
	v_mfma_f32_16x16x32_bf16 v[40:43], v[158:161], v[130:133], v[40:43]
	global_store_dwordx4 v[100:101], v[56:59], off
	s_nop 1
	v_pk_mul_f32 v[56:57], v[48:49], v[48:49]
	v_max_f32_e32 v49, v50, v50
	v_max_f32_e32 v48, v54, v54
	v_max_f32_e32 v50, 0, v49
	v_max_f32_e32 v49, v55, v55
	v_mfma_f32_16x16x32_bf16 v[44:47], v[154:157], v[130:133], v[44:47]
	v_max_f32_e32 v48, 0, v48
	v_max_f32_e32 v49, 0, v49
	v_pk_mul_f32 v[54:55], v[48:49], v[48:49]
	v_pk_mul_f32 v[58:59], v[50:51], v[50:51]
	v_max_f32_e32 v40, v40, v40
	v_max_f32_e32 v41, v41, v41
	s_waitcnt lgkmcnt(0)
	v_mfma_f32_16x16x32_bf16 v[32:35], v[162:165], v[130:133], v[32:35]
	v_cvt_pk_bf16_f32 v48, v52, v53
	v_cvt_pk_bf16_f32 v49, v54, v55
	v_cvt_pk_bf16_f32 v50, v56, v57
	v_cvt_pk_bf16_f32 v51, v58, v59
	v_max_f32_e32 v40, 0, v40
	v_max_f32_e32 v41, 0, v41
	global_store_dwordx4 v[100:101], v[48:51], off offset:64
	v_max_f32_e32 v44, v44, v44
	v_max_f32_e32 v45, v45, v45
	v_pk_mul_f32 v[48:49], v[40:41], v[40:41]
	v_max_f32_e32 v41, v42, v42
	v_max_f32_e32 v40, v46, v46
	v_max_f32_e32 v42, 0, v41
	v_max_f32_e32 v41, v47, v47
	v_max_f32_e32 v43, v43, v43
	v_mfma_f32_16x16x32_bf16 v[36:39], v[74:77], v[130:133], v[36:39]
	v_max_f32_e32 v44, 0, v44
	v_max_f32_e32 v45, 0, v45
	v_max_f32_e32 v40, 0, v40
	v_max_f32_e32 v41, 0, v41
	v_max_f32_e32 v43, 0, v43
	v_pk_mul_f32 v[44:45], v[44:45], v[44:45]
	v_pk_mul_f32 v[46:47], v[40:41], v[40:41]
	v_pk_mul_f32 v[50:51], v[42:43], v[42:43]
	v_max_f32_e32 v32, v32, v32
	v_max_f32_e32 v33, v33, v33
	v_mfma_f32_16x16x32_bf16 v[24:27], v[146:149], v[134:137], v[24:27]
	v_cvt_pk_bf16_f32 v40, v44, v45
	v_cvt_pk_bf16_f32 v41, v46, v47
	v_cvt_pk_bf16_f32 v42, v48, v49
	v_cvt_pk_bf16_f32 v43, v50, v51
	v_max_f32_e32 v32, 0, v32
	v_max_f32_e32 v33, 0, v33
	global_store_dwordx4 v[100:101], v[40:43], off offset:128
	v_max_f32_e32 v36, v36, v36
	v_max_f32_e32 v37, v37, v37
	v_pk_mul_f32 v[40:41], v[32:33], v[32:33]
	v_max_f32_e32 v33, v34, v34
	v_max_f32_e32 v32, v38, v38
	v_max_f32_e32 v34, 0, v33
	v_max_f32_e32 v33, v39, v39
	v_max_f32_e32 v35, v35, v35
	v_mfma_f32_16x16x32_bf16 v[28:31], v[138:141], v[134:137], v[28:31]
	v_max_f32_e32 v36, 0, v36
	v_max_f32_e32 v37, 0, v37
	v_max_f32_e32 v32, 0, v32
	v_max_f32_e32 v33, 0, v33
	v_max_f32_e32 v35, 0, v35
	v_pk_mul_f32 v[36:37], v[36:37], v[36:37]
	v_pk_mul_f32 v[38:39], v[32:33], v[32:33]
	v_pk_mul_f32 v[42:43], v[34:35], v[34:35]
	v_max_f32_e32 v24, v24, v24
	v_max_f32_e32 v25, v25, v25
	v_mfma_f32_16x16x32_bf16 v[12:15], v[150:153], v[134:137], v[12:15]
	v_cvt_pk_bf16_f32 v32, v36, v37
	v_cvt_pk_bf16_f32 v33, v38, v39
	v_cvt_pk_bf16_f32 v34, v40, v41
	v_cvt_pk_bf16_f32 v35, v42, v43
	v_max_f32_e32 v24, 0, v24
	v_max_f32_e32 v25, 0, v25
	global_store_dwordx4 v[100:101], v[32:35], off offset:192
	v_max_f32_e32 v28, v28, v28
	v_max_f32_e32 v29, v29, v29
	v_pk_mul_f32 v[34:35], v[24:25], v[24:25]
	v_max_f32_e32 v25, v26, v26
	v_add_u32_e32 v32, s36, v84
	v_max_f32_e32 v24, v30, v30
	v_max_f32_e32 v26, 0, v25
	v_max_f32_e32 v25, v31, v31
	v_max_f32_e32 v27, v27, v27
	v_mfma_f32_16x16x32_bf16 v[16:19], v[94:97], v[134:137], v[16:19]
	v_mad_i64_i32 v[32:33], s[34:35], v32, s30, v[98:99]
	v_max_f32_e32 v28, 0, v28
	v_max_f32_e32 v29, 0, v29
	v_max_f32_e32 v24, 0, v24
	v_max_f32_e32 v25, 0, v25
	v_max_f32_e32 v27, 0, v27
	v_lshl_add_u64 v[32:33], v[32:33], 0, s[26:27]
	v_pk_mul_f32 v[28:29], v[28:29], v[28:29]
	v_pk_mul_f32 v[30:31], v[24:25], v[24:25]
	v_pk_mul_f32 v[36:37], v[26:27], v[26:27]
	v_max_f32_e32 v12, v12, v12
	v_max_f32_e32 v13, v13, v13
	v_mfma_f32_16x16x32_bf16 v[4:7], v[158:161], v[134:137], v[4:7]
	v_lshl_add_u64 v[32:33], v[32:33], 0, v[64:65]
	v_cvt_pk_bf16_f32 v24, v28, v29
	v_cvt_pk_bf16_f32 v25, v30, v31
	v_cvt_pk_bf16_f32 v26, v34, v35
	v_cvt_pk_bf16_f32 v27, v36, v37
	v_max_f32_e32 v12, 0, v12
	v_max_f32_e32 v13, 0, v13
	global_store_dwordx4 v[32:33], v[24:27], off
	v_max_f32_e32 v16, v16, v16
	v_max_f32_e32 v17, v17, v17
	v_pk_mul_f32 v[24:25], v[12:13], v[12:13]
	v_max_f32_e32 v13, v14, v14
	v_max_f32_e32 v12, v18, v18
	v_max_f32_e32 v14, 0, v13
	v_max_f32_e32 v13, v19, v19
	v_max_f32_e32 v15, v15, v15
	v_mfma_f32_16x16x32_bf16 v[8:11], v[154:157], v[134:137], v[8:11]
	v_max_f32_e32 v16, 0, v16
	v_max_f32_e32 v17, 0, v17
	v_max_f32_e32 v12, 0, v12
	v_max_f32_e32 v13, 0, v13
	v_max_f32_e32 v15, 0, v15
	v_pk_mul_f32 v[16:17], v[16:17], v[16:17]
	v_pk_mul_f32 v[18:19], v[12:13], v[12:13]
	v_pk_mul_f32 v[26:27], v[14:15], v[14:15]
	v_max_f32_e32 v4, v4, v4
	v_max_f32_e32 v5, v5, v5
	v_cvt_pk_bf16_f32 v12, v16, v17
	v_cvt_pk_bf16_f32 v13, v18, v19
	v_cvt_pk_bf16_f32 v14, v24, v25
	v_cvt_pk_bf16_f32 v15, v26, v27
	v_max_f32_e32 v4, 0, v4
	v_max_f32_e32 v5, 0, v5
	global_store_dwordx4 v[32:33], v[12:15], off offset:64
	v_mfma_f32_16x16x32_bf16 v[0:3], v[74:77], v[134:137], v[0:3]
	v_max_f32_e32 v8, v8, v8
	v_pk_mul_f32 v[12:13], v[4:5], v[4:5]
	v_max_f32_e32 v5, v6, v6
	v_mfma_f32_16x16x32_bf16 v[20:23], v[162:165], v[134:137], v[20:23]
	v_max_f32_e32 v9, v9, v9
	v_max_f32_e32 v4, v10, v10
	v_max_f32_e32 v6, 0, v5
	v_max_f32_e32 v5, v11, v11
	v_max_f32_e32 v7, v7, v7
	v_max_f32_e32 v8, 0, v8
	v_max_f32_e32 v9, 0, v9
	v_max_f32_e32 v4, 0, v4
	v_max_f32_e32 v5, 0, v5
	v_max_f32_e32 v7, 0, v7
	v_pk_mul_f32 v[8:9], v[8:9], v[8:9]
	v_pk_mul_f32 v[10:11], v[4:5], v[4:5]
	v_pk_mul_f32 v[14:15], v[6:7], v[6:7]
	v_cvt_pk_bf16_f32 v4, v8, v9
	v_cvt_pk_bf16_f32 v5, v10, v11
	v_cvt_pk_bf16_f32 v6, v12, v13
	v_cvt_pk_bf16_f32 v7, v14, v15
	global_store_dwordx4 v[32:33], v[4:7], off offset:128
	v_max_f32_e32 v0, v0, v0
	v_max_f32_e32 v1, v1, v1
	v_max_f32_e32 v4, v20, v20
	v_max_f32_e32 v5, v21, v21
	v_max_f32_e32 v2, v2, v2
	v_max_f32_e32 v6, v22, v22
	v_max_f32_e32 v3, v3, v3
	v_max_f32_e32 v7, v23, v23
	v_max_f32_e32 v0, 0, v0
	v_max_f32_e32 v4, 0, v4
	v_max_f32_e32 v1, 0, v1
	v_max_f32_e32 v5, 0, v5
	v_max_f32_e32 v2, 0, v2
	v_max_f32_e32 v6, 0, v6
	v_max_f32_e32 v3, 0, v3
	v_max_f32_e32 v7, 0, v7
	v_pk_mul_f32 v[0:1], v[0:1], v[0:1]
	v_pk_mul_f32 v[4:5], v[4:5], v[4:5]
	v_pk_mul_f32 v[2:3], v[2:3], v[2:3]
	v_pk_mul_f32 v[6:7], v[6:7], v[6:7]
	v_cvt_pk_bf16_f32 v0, v0, v1
	v_cvt_pk_bf16_f32 v1, v2, v3
	v_cvt_pk_bf16_f32 v2, v4, v5
	v_cvt_pk_bf16_f32 v3, v6, v7
	global_store_dwordx4 v[32:33], v[0:3], off offset:192
	s_cbranch_scc0 .LBB0_1005

.LBB0_1071:
	s_add_i32 s45, s43, 0x8000
	s_and_b32 s44, s45, 0x8000
	s_add_i32 s44, s44, 0
	s_add_u32 s86, s44, s87
	s_mov_b32 m0, s86
	s_waitcnt vmcnt(0) lgkmcnt(0)
	s_barrier
	global_load_lds_dwordx4 v244, s[96:97]
	s_add_u32 m0, s86, 0x1000
	s_nop 0
	global_load_lds_dwordx4 v246, s[96:97]
	s_add_u32 m0, s86, 0x2000
	s_nop 0
	global_load_lds_dwordx4 v248, s[96:97]
	s_add_u32 m0, s86, 0x3000
	s_nop 0
	global_load_lds_dwordx4 v250, s[96:97]
	s_add_u32 m0, s86, 0x4000
	s_nop 0
	global_load_lds_dwordx4 v245, s[88:89]
	s_add_u32 m0, s86, 0x5000
	s_nop 0
	global_load_lds_dwordx4 v247, s[88:89]
	s_add_u32 m0, s86, 0x6000
	s_nop 0
	global_load_lds_dwordx4 v249, s[88:89]
	s_add_u32 m0, s86, 0x7000
	s_nop 0
	global_load_lds_dwordx4 v251, s[88:89]
	s_add_u32 s96, s96, 0x80
	s_addc_u32 s97, s97, 0
	s_add_u32 s88, s88, 0x80
	s_addc_u32 s89, s89, 0
	s_and_b32 s43, s43, 0x8000
	s_add_i32 s43, s43, 0
	v_add3_u32 v169, s43, v84, v89
	v_add3_u32 v210, s43, v89, v90
	v_add3_u32 v211, s43, v84, v91
	v_add3_u32 v212, s43, v90, v91
	ds_read_b128 v[106:109], v210
	ds_read_b128 v[76:79], v169 offset:16384
	ds_read_b128 v[102:105], v169 offset:18432
	ds_read_b128 v[110:113], v210 offset:2048
	ds_read_b128 v[114:117], v169 offset:20480
	ds_read_b128 v[118:121], v169 offset:22528
	ds_read_b128 v[122:125], v169 offset:24576
	ds_read_b128 v[126:129], v169 offset:26624
	ds_read_b128 v[130:133], v169 offset:28672
	ds_read_b128 v[134:137], v169 offset:30720
	ds_read_b128 v[178:181], v212
	ds_read_b128 v[170:173], v211 offset:16384
	ds_read_b128 v[174:177], v211 offset:18432
	ds_read_b128 v[182:185], v212 offset:2048
	ds_read_b128 v[186:189], v211 offset:20480
	ds_read_b128 v[190:193], v211 offset:22528
	ds_read_b128 v[194:197], v211 offset:24576
	ds_read_b128 v[198:201], v211 offset:26624
	ds_read_b128 v[202:205], v211 offset:28672
	ds_read_b128 v[206:209], v211 offset:30720
	s_add_u32 s34, s34, 0x80
	s_addc_u32 s35, s35, 0
	s_cmpk_eq_i32 s34, 0x1f80
	s_mov_b32 s43, s45
	s_waitcnt lgkmcnt(15)
	v_mfma_f32_16x16x32_bf16 v[60:63], v[76:79], v[106:109], v[60:63]
	v_mfma_f32_16x16x32_bf16 v[56:59], v[102:105], v[106:109], v[56:59]
	v_mfma_f32_16x16x32_bf16 v[24:27], v[76:79], v[110:113], v[24:27]
	v_mfma_f32_16x16x32_bf16 v[20:23], v[102:105], v[110:113], v[20:23]
	v_mfma_f32_16x16x32_bf16 v[52:55], v[114:117], v[106:109], v[52:55]
	v_mfma_f32_16x16x32_bf16 v[16:19], v[114:117], v[110:113], v[16:19]
	s_waitcnt lgkmcnt(14)
	v_mfma_f32_16x16x32_bf16 v[48:51], v[118:121], v[106:109], v[48:51]
	v_mfma_f32_16x16x32_bf16 v[12:15], v[118:121], v[110:113], v[12:15]
	s_waitcnt lgkmcnt(13)
	v_mfma_f32_16x16x32_bf16 v[44:47], v[122:125], v[106:109], v[44:47]
	v_mfma_f32_16x16x32_bf16 v[8:11], v[122:125], v[110:113], v[8:11]
	s_waitcnt lgkmcnt(12)
	v_mfma_f32_16x16x32_bf16 v[40:43], v[126:129], v[106:109], v[40:43]
	v_mfma_f32_16x16x32_bf16 v[4:7], v[126:129], v[110:113], v[4:7]
	s_waitcnt lgkmcnt(11)
	v_mfma_f32_16x16x32_bf16 v[32:35], v[130:133], v[106:109], v[32:35]
	v_mfma_f32_16x16x32_bf16 v[0:3], v[130:133], v[110:113], v[0:3]
	s_waitcnt lgkmcnt(10)
	v_mfma_f32_16x16x32_bf16 v[28:31], v[134:137], v[106:109], v[28:31]
	v_mfma_f32_16x16x32_bf16 v[36:39], v[134:137], v[110:113], v[36:39]
	s_waitcnt lgkmcnt(8)
	v_mfma_f32_16x16x32_bf16 v[60:63], v[170:173], v[178:181], v[60:63]
	s_waitcnt lgkmcnt(7)
	v_mfma_f32_16x16x32_bf16 v[56:59], v[174:177], v[178:181], v[56:59]
	s_waitcnt lgkmcnt(6)
	v_mfma_f32_16x16x32_bf16 v[24:27], v[170:173], v[182:185], v[24:27]
	v_mfma_f32_16x16x32_bf16 v[20:23], v[174:177], v[182:185], v[20:23]
	s_waitcnt lgkmcnt(5)
	v_mfma_f32_16x16x32_bf16 v[52:55], v[186:189], v[178:181], v[52:55]
	v_mfma_f32_16x16x32_bf16 v[16:19], v[186:189], v[182:185], v[16:19]
	s_waitcnt lgkmcnt(4)
	v_mfma_f32_16x16x32_bf16 v[48:51], v[190:193], v[178:181], v[48:51]
	v_mfma_f32_16x16x32_bf16 v[12:15], v[190:193], v[182:185], v[12:15]
	s_waitcnt lgkmcnt(3)
	v_mfma_f32_16x16x32_bf16 v[44:47], v[194:197], v[178:181], v[44:47]
	v_mfma_f32_16x16x32_bf16 v[8:11], v[194:197], v[182:185], v[8:11]
	s_waitcnt lgkmcnt(2)
	v_mfma_f32_16x16x32_bf16 v[40:43], v[198:201], v[178:181], v[40:43]
	v_mfma_f32_16x16x32_bf16 v[4:7], v[198:201], v[182:185], v[4:7]
	s_waitcnt lgkmcnt(1)
	v_mfma_f32_16x16x32_bf16 v[32:35], v[202:205], v[178:181], v[32:35]
	v_mfma_f32_16x16x32_bf16 v[0:3], v[202:205], v[182:185], v[0:3]
	s_waitcnt lgkmcnt(0)
	v_mfma_f32_16x16x32_bf16 v[28:31], v[206:209], v[178:181], v[28:31]
	v_mfma_f32_16x16x32_bf16 v[36:39], v[206:209], v[182:185], v[36:39]
	s_cbranch_scc0 .LBB0_1071
	v_add_u32_e32 v80, s44, v84
	v_add_u32_e32 v81, v80, v89
	v_add3_u32 v106, s44, v89, v90
	s_waitcnt vmcnt(0)
	s_barrier
	ds_read_b128 v[72:75], v81 offset:16384
	ds_read_b128 v[76:79], v81 offset:18432
	ds_read_b128 v[102:105], v106
	ds_read_b128 v[106:109], v106 offset:2048
	ds_read_b128 v[110:113], v81 offset:20480
	ds_read_b128 v[114:117], v81 offset:22528
	ds_read_b128 v[118:121], v81 offset:24576
	ds_read_b128 v[122:125], v81 offset:26624
	ds_read_b128 v[126:129], v81 offset:28672
	ds_read_b128 v[130:133], v81 offset:30720
	v_add_u32_e32 v80, v80, v91
	s_waitcnt lgkmcnt(7)
	v_mfma_f32_16x16x32_bf16 v[60:63], v[72:75], v[102:105], v[60:63]
	s_lshl_b32 s42, s42, 7
	v_mfma_f32_16x16x32_bf16 v[56:59], v[76:79], v[102:105], v[56:59]
	s_waitcnt lgkmcnt(4)
	v_mfma_f32_16x16x32_bf16 v[48:51], v[114:117], v[102:105], v[48:51]
	s_waitcnt lgkmcnt(3)
	v_mfma_f32_16x16x32_bf16 v[44:47], v[118:121], v[102:105], v[44:47]
	s_waitcnt lgkmcnt(2)
	v_mfma_f32_16x16x32_bf16 v[40:43], v[122:125], v[102:105], v[40:43]
	s_waitcnt lgkmcnt(1)
	v_mfma_f32_16x16x32_bf16 v[32:35], v[126:129], v[102:105], v[32:35]
	s_waitcnt lgkmcnt(0)
	v_mfma_f32_16x16x32_bf16 v[28:31], v[130:133], v[102:105], v[28:31]
	v_mfma_f32_16x16x32_bf16 v[24:27], v[72:75], v[106:109], v[24:27]
	ds_read_b128 v[72:75], v80 offset:16384
	v_mfma_f32_16x16x32_bf16 v[52:55], v[110:113], v[102:105], v[52:55]
	v_mfma_f32_16x16x32_bf16 v[20:23], v[76:79], v[106:109], v[20:23]
	v_mfma_f32_16x16x32_bf16 v[16:19], v[110:113], v[106:109], v[16:19]
	v_mfma_f32_16x16x32_bf16 v[12:15], v[114:117], v[106:109], v[12:15]
	v_mfma_f32_16x16x32_bf16 v[8:11], v[118:121], v[106:109], v[8:11]
	v_mfma_f32_16x16x32_bf16 v[4:7], v[122:125], v[106:109], v[4:7]
	v_mfma_f32_16x16x32_bf16 v[0:3], v[126:129], v[106:109], v[0:3]
	v_mfma_f32_16x16x32_bf16 v[102:105], v[130:133], v[106:109], v[36:39]
	s_nop 2
	v_add3_u32 v36, s44, v91, v90
	ds_read_b128 v[76:79], v80 offset:18432
	ds_read_b128 v[106:109], v36
	ds_read_b128 v[110:113], v36 offset:2048
	ds_read_b128 v[130:133], v80 offset:28672
	ds_read_b128 v[134:137], v80 offset:30720
	ds_read_b128 v[114:117], v80 offset:20480
	ds_read_b128 v[118:121], v80 offset:22528
	ds_read_b128 v[122:125], v80 offset:24576
	ds_read_b128 v[126:129], v80 offset:26624
	s_waitcnt lgkmcnt(7)
	v_mfma_f32_16x16x32_bf16 v[60:63], v[72:75], v[106:109], v[60:63]
	s_waitcnt lgkmcnt(5)
	v_mfma_f32_16x16x32_bf16 v[36:39], v[130:133], v[106:109], v[32:35]
	s_waitcnt lgkmcnt(4)
	v_mfma_f32_16x16x32_bf16 v[32:35], v[134:137], v[106:109], v[28:31]
	v_mfma_f32_16x16x32_bf16 v[28:31], v[72:75], v[110:113], v[24:27]
	v_add_u32_e32 v72, s42, v85
	v_mul_hi_i32 v73, v72, s36
	v_mfma_f32_16x16x32_bf16 v[24:27], v[76:79], v[110:113], v[20:23]
	s_waitcnt lgkmcnt(3)
	v_mfma_f32_16x16x32_bf16 v[20:23], v[114:117], v[110:113], v[16:19]
	s_waitcnt lgkmcnt(2)
	v_mfma_f32_16x16x32_bf16 v[16:19], v[118:121], v[110:113], v[12:15]
	s_waitcnt lgkmcnt(1)
	v_mfma_f32_16x16x32_bf16 v[12:15], v[122:125], v[110:113], v[8:11]
	s_waitcnt lgkmcnt(0)
	v_mfma_f32_16x16x32_bf16 v[8:11], v[126:129], v[110:113], v[4:7]
	s_nop 2
	v_lshrrev_b32_e32 v4, 31, v73
	v_ashrrev_i32_e32 v5, 11, v73
	v_mfma_f32_16x16x32_bf16 v[56:59], v[76:79], v[106:109], v[56:59]
	v_add_u32_e32 v73, v5, v4
	v_mad_i32_i24 v78, v73, s37, v72
	v_lshlrev_b32_e32 v75, 13, v73
	v_mfma_f32_16x16x32_bf16 v[52:55], v[114:117], v[106:109], v[52:55]
	v_cmp_lt_i32_e32 vcc, s38, v78
	v_add3_u32 v74, v75, v78, s39
	v_mfma_f32_16x16x32_bf16 v[48:51], v[118:121], v[106:109], v[48:51]
	v_mfma_f32_16x16x32_bf16 v[44:47], v[122:125], v[106:109], v[44:47]
	v_mfma_f32_16x16x32_bf16 v[40:43], v[126:129], v[106:109], v[40:43]
	v_mfma_f32_16x16x32_bf16 v[4:7], v[130:133], v[110:113], v[0:3]
	v_mfma_f32_16x16x32_bf16 v[0:3], v[134:137], v[110:113], v[102:105]
	s_and_saveexec_b64 s[34:35], vcc
	s_xor_b64 s[34:35], exec, s[34:35]
	v_add3_u32 v72, v75, v78, s39
	s_or_saveexec_b64 s[34:35], s[34:35]
	v_mov_b64_e32 v[76:77], s[92:93]
	v_lshl_add_u32 v75, v73, 8, v78
	s_xor_b64 exec, exec, s[34:35]
	v_lshl_add_u32 v72, v73, 8, v78
	v_mov_b64_e32 v[76:77], s[6:7]
	s_or_b64 exec, exec, s[34:35]
	s_and_saveexec_b64 s[34:35], vcc
	s_xor_b64 s[34:35], exec, s[34:35]
	s_cbranch_execz .LBB0_1078
	v_mul_hi_i32_i24_e32 v79, 0x6000, v73
	v_mul_i32_i24_e32 v78, 0x6000, v73
	s_or_saveexec_b64 s[34:35], s[34:35]
	v_mov_b64_e32 v[80:81], s[92:93]
	s_xor_b64 exec, exec, s[34:35]
	s_cbranch_execnz .LBB0_1079
	s_branch .LBB0_1080

.LBB0_1091:
	s_add_i32 s48, s47, 0x8000
	s_and_b32 s8, s47, 0x8000
	s_and_b32 s47, s48, 0x8000
	s_add_i32 s49, s8, 0
	s_add_i32 s8, s47, 0
	s_add_u32 s71, s8, s75
	s_mov_b32 m0, s71
	s_waitcnt vmcnt(0) lgkmcnt(0)
	s_barrier
	global_load_lds_dwordx4 v236, s[84:85]
	s_add_u32 m0, s71, 0x1000
	s_nop 0
	global_load_lds_dwordx4 v238, s[84:85]
	s_add_u32 m0, s71, 0x2000
	s_nop 0
	global_load_lds_dwordx4 v240, s[84:85]
	s_add_u32 m0, s71, 0x3000
	s_nop 0
	global_load_lds_dwordx4 v242, s[84:85]
	s_add_u32 m0, s71, 0x4000
	s_nop 0
	global_load_lds_dwordx4 v237, s[72:73]
	s_add_u32 m0, s71, 0x5000
	s_nop 0
	global_load_lds_dwordx4 v239, s[72:73]
	s_add_u32 m0, s71, 0x6000
	s_nop 0
	global_load_lds_dwordx4 v241, s[72:73]
	s_add_u32 m0, s71, 0x7000
	s_nop 0
	global_load_lds_dwordx4 v243, s[72:73]
	s_add_u32 s84, s84, 0x80
	s_addc_u32 s85, s85, 0
	s_add_u32 s72, s72, 0x80
	s_addc_u32 s73, s73, 0
	v_add3_u32 v169, s49, v84, v87
	v_add3_u32 v210, s49, v87, v89
	v_add3_u32 v211, s49, v84, v90
	v_add3_u32 v212, s49, v89, v90
	ds_read_b128 v[104:107], v210
	ds_read_b128 v[68:71], v169 offset:16384
	ds_read_b128 v[100:103], v169 offset:18432
	ds_read_b128 v[108:111], v210 offset:2048
	ds_read_b128 v[112:115], v169 offset:20480
	ds_read_b128 v[116:119], v169 offset:22528
	ds_read_b128 v[120:123], v169 offset:24576
	ds_read_b128 v[124:127], v169 offset:26624
	ds_read_b128 v[128:131], v169 offset:28672
	ds_read_b128 v[132:135], v169 offset:30720
	ds_read_b128 v[178:181], v212
	ds_read_b128 v[170:173], v211 offset:16384
	ds_read_b128 v[174:177], v211 offset:18432
	ds_read_b128 v[182:185], v212 offset:2048
	ds_read_b128 v[186:189], v211 offset:20480
	ds_read_b128 v[190:193], v211 offset:22528
	ds_read_b128 v[194:197], v211 offset:24576
	ds_read_b128 v[198:201], v211 offset:26624
	ds_read_b128 v[202:205], v211 offset:28672
	ds_read_b128 v[206:209], v211 offset:30720
	s_add_u32 s36, s36, 0x80
	s_addc_u32 s37, s37, 0
	s_cmpk_eq_i32 s36, 0x780
	s_mov_b32 s47, s48
	s_waitcnt lgkmcnt(15)
	v_mfma_f32_16x16x32_bf16 v[60:63], v[68:71], v[104:107], v[60:63]
	v_mfma_f32_16x16x32_bf16 v[56:59], v[100:103], v[104:107], v[56:59]
	v_mfma_f32_16x16x32_bf16 v[28:31], v[68:71], v[108:111], v[28:31]
	v_mfma_f32_16x16x32_bf16 v[24:27], v[100:103], v[108:111], v[24:27]
	v_mfma_f32_16x16x32_bf16 v[52:55], v[112:115], v[104:107], v[52:55]
	v_mfma_f32_16x16x32_bf16 v[16:19], v[112:115], v[108:111], v[16:19]
	s_waitcnt lgkmcnt(14)
	v_mfma_f32_16x16x32_bf16 v[48:51], v[116:119], v[104:107], v[48:51]
	v_mfma_f32_16x16x32_bf16 v[12:15], v[116:119], v[108:111], v[12:15]
	s_waitcnt lgkmcnt(13)
	v_mfma_f32_16x16x32_bf16 v[44:47], v[120:123], v[104:107], v[44:47]
	v_mfma_f32_16x16x32_bf16 v[8:11], v[120:123], v[108:111], v[8:11]
	s_waitcnt lgkmcnt(12)
	v_mfma_f32_16x16x32_bf16 v[40:43], v[124:127], v[104:107], v[40:43]
	v_mfma_f32_16x16x32_bf16 v[4:7], v[124:127], v[108:111], v[4:7]
	s_waitcnt lgkmcnt(11)
	v_mfma_f32_16x16x32_bf16 v[36:39], v[128:131], v[104:107], v[36:39]
	v_mfma_f32_16x16x32_bf16 v[0:3], v[128:131], v[108:111], v[0:3]
	s_waitcnt lgkmcnt(10)
	v_mfma_f32_16x16x32_bf16 v[32:35], v[132:135], v[104:107], v[32:35]
	v_mfma_f32_16x16x32_bf16 v[20:23], v[132:135], v[108:111], v[20:23]
	s_waitcnt lgkmcnt(8)
	v_mfma_f32_16x16x32_bf16 v[60:63], v[170:173], v[178:181], v[60:63]
	s_waitcnt lgkmcnt(7)
	v_mfma_f32_16x16x32_bf16 v[56:59], v[174:177], v[178:181], v[56:59]
	s_waitcnt lgkmcnt(6)
	v_mfma_f32_16x16x32_bf16 v[28:31], v[170:173], v[182:185], v[28:31]
	v_mfma_f32_16x16x32_bf16 v[24:27], v[174:177], v[182:185], v[24:27]
	s_waitcnt lgkmcnt(5)
	v_mfma_f32_16x16x32_bf16 v[52:55], v[186:189], v[178:181], v[52:55]
	v_mfma_f32_16x16x32_bf16 v[16:19], v[186:189], v[182:185], v[16:19]
	s_waitcnt lgkmcnt(4)
	v_mfma_f32_16x16x32_bf16 v[48:51], v[190:193], v[178:181], v[48:51]
	v_mfma_f32_16x16x32_bf16 v[12:15], v[190:193], v[182:185], v[12:15]
	s_waitcnt lgkmcnt(3)
	v_mfma_f32_16x16x32_bf16 v[44:47], v[194:197], v[178:181], v[44:47]
	v_mfma_f32_16x16x32_bf16 v[8:11], v[194:197], v[182:185], v[8:11]
	s_waitcnt lgkmcnt(2)
	v_mfma_f32_16x16x32_bf16 v[40:43], v[198:201], v[178:181], v[40:43]
	v_mfma_f32_16x16x32_bf16 v[4:7], v[198:201], v[182:185], v[4:7]
	s_waitcnt lgkmcnt(1)
	v_mfma_f32_16x16x32_bf16 v[36:39], v[202:205], v[178:181], v[36:39]
	v_mfma_f32_16x16x32_bf16 v[0:3], v[202:205], v[182:185], v[0:3]
	s_waitcnt lgkmcnt(0)
	v_mfma_f32_16x16x32_bf16 v[32:35], v[206:209], v[178:181], v[32:35]
	v_mfma_f32_16x16x32_bf16 v[20:23], v[206:209], v[182:185], v[20:23]
	s_cbranch_scc0 .LBB0_1091
	v_lshl_add_u32 v99, s46, 7, v85
	v_mul_hi_i32 v64, v99, s39
	v_lshrrev_b32_e32 v65, 31, v64
	v_ashrrev_i32_e32 v64, 11, v64
	v_add_u32_e32 v64, v64, v65
	v_mad_i32_i24 v65, v64, s40, v99
	v_cmp_lt_i32_e32 vcc, s41, v65
	v_lshl_or_b32 v72, s45, 9, v86
	s_waitcnt vmcnt(0)
	v_cndmask_b32_e32 v64, 2, v64, vcc
	v_mul_hi_i32_i24_e32 v65, 0x6000, v64
	v_mul_i32_i24_e32 v64, 0x6000, v64
	v_lshl_add_u64 v[64:65], s[94:95], 0, v[64:65]
	v_lshl_add_u64 v[150:151], v[64:65], 0, s[34:35]
	v_lshl_add_u64 v[64:65], v[150:151], 0, v[72:73]
	s_barrier
	global_load_dwordx4 v[100:103], v[64:65], off
	v_add3_u32 v64, s8, v87, v89
	v_add_u32_e32 v68, s8, v84
	ds_read_b128 v[104:107], v64
	ds_read_b128 v[108:111], v64 offset:2048
	v_add3_u32 v65, s8, v90, v89
	v_add_u32_e32 v145, v68, v87
	ds_read_b128 v[112:115], v65
	ds_read_b128 v[64:67], v65 offset:2048
	v_add_u32_e32 v168, v68, v90
	ds_read_b128 v[116:119], v145 offset:16384
	ds_read_b128 v[120:123], v145 offset:18432
	ds_read_b128 v[124:127], v168 offset:16384
	ds_read_b128 v[68:71], v168 offset:18432
	v_mul_hi_i32 v128, v99, s38
	s_waitcnt lgkmcnt(3)
	v_mfma_f32_16x16x32_bf16 v[60:63], v[116:119], v[104:107], v[60:63]
	v_lshrrev_b32_e32 v129, 31, v128
	v_lshrrev_b32_e32 v128, 11, v128
	v_add_u32_e32 v128, v128, v129
	v_lshl_add_u32 v128, v128, 13, v99
	s_lshl_b32 s8, s44, 9
	v_ashrrev_i32_e32 v129, 31, v128
	s_waitcnt lgkmcnt(1)
	v_mfma_f32_16x16x32_bf16 v[60:63], v[124:127], v[112:115], v[60:63]
	v_lshl_add_u64 v[128:129], v[128:129], 0, s[8:9]
	v_lshlrev_b64 v[128:129], 12, v[128:129]
	v_lshl_add_u64 v[128:129], s[6:7], 0, v[128:129]
	v_mov_b32_e32 v153, v73
	v_or_b32_e32 v152, 16, v72
	v_lshl_add_u64 v[154:155], v[128:129], 0, v[72:73]
	v_lshl_add_u64 v[128:129], v[150:151], 0, v[152:153]
	v_mfma_f32_16x16x32_bf16 v[56:59], v[120:123], v[104:107], v[56:59]
	v_mov_b32_e32 v157, v73
	v_or_b32_e32 v156, 0x80, v72
	v_mov_b32_e32 v159, v73
	s_waitcnt lgkmcnt(0)
	v_mfma_f32_16x16x32_bf16 v[56:59], v[68:71], v[112:115], v[56:59]
	v_or_b32_e32 v158, 0x90, v72
	v_lshl_add_u64 v[136:137], v[150:151], 0, v[158:159]
	v_mov_b32_e32 v161, v73
	v_or_b32_e32 v160, 0x100, v72
	v_mov_b32_e32 v163, v73
	v_or_b32_e32 v162, 0x110, v72
	v_lshl_add_u64 v[146:147], v[150:151], 0, v[162:163]
	v_mov_b32_e32 v165, v73
	v_or_b32_e32 v164, 0x180, v72
	v_lshl_add_u64 v[166:167], v[150:151], 0, v[164:165]
	v_mfma_f32_16x16x32_bf16 v[28:31], v[116:119], v[108:111], v[28:31]
	v_or_b32_e32 v99, 16, v99
	s_add_i32 s43, s43, s33
	s_add_i32 s42, s42, s33
	v_mfma_f32_16x16x32_bf16 v[28:31], v[124:127], v[64:67], v[28:31]
	s_cmpk_gt_i32 s43, 0x7f
	s_waitcnt vmcnt(0)
	v_pk_mul_f32 v[62:63], v[62:63], v[102:103]
	v_pk_mul_f32 v[60:61], v[60:61], v[100:101]
	global_store_dwordx4 v[154:155], v[60:63], off
	global_load_dwordx4 v[60:63], v[128:129], off
	v_lshl_add_u64 v[100:101], v[150:151], 0, v[156:157]
	v_mfma_f32_16x16x32_bf16 v[24:27], v[120:123], v[108:111], v[24:27]
	s_waitcnt vmcnt(0)
	v_pk_mul_f32 v[58:59], v[58:59], v[62:63]
	v_pk_mul_f32 v[56:57], v[56:57], v[60:61]
	global_store_dwordx4 v[154:155], v[56:59], off offset:16
	global_load_dwordx4 v[56:59], v[100:101], off
	ds_read_b128 v[60:63], v145 offset:20480
	ds_read_b128 v[100:103], v168 offset:20480
	s_waitcnt lgkmcnt(1)
	v_mfma_f32_16x16x32_bf16 v[52:55], v[60:63], v[104:107], v[52:55]
	ds_read_b128 v[128:131], v145 offset:22528
	ds_read_b128 v[132:135], v168 offset:22528
	s_waitcnt lgkmcnt(2)
	v_mfma_f32_16x16x32_bf16 v[52:55], v[100:103], v[112:115], v[52:55]
	s_waitcnt lgkmcnt(1)
	v_mfma_f32_16x16x32_bf16 v[48:51], v[128:131], v[104:107], v[48:51]
	s_waitcnt vmcnt(0)
	s_nop 4
	v_pk_mul_f32 v[54:55], v[54:55], v[58:59]
	v_pk_mul_f32 v[52:53], v[52:53], v[56:57]
	global_store_dwordx4 v[154:155], v[52:55], off offset:128
	global_load_dwordx4 v[52:55], v[136:137], off
	s_waitcnt lgkmcnt(0)
	v_mfma_f32_16x16x32_bf16 v[48:51], v[132:135], v[112:115], v[48:51]
	v_lshl_add_u64 v[56:57], v[150:151], 0, v[160:161]
	v_mfma_f32_16x16x32_bf16 v[24:27], v[68:71], v[64:67], v[24:27]
	v_mfma_f32_16x16x32_bf16 v[16:19], v[60:63], v[108:111], v[16:19]
	s_waitcnt vmcnt(0)
	s_nop 3
	v_pk_mul_f32 v[50:51], v[50:51], v[54:55]
	v_pk_mul_f32 v[48:49], v[48:49], v[52:53]
	global_store_dwordx4 v[154:155], v[48:51], off offset:144
	global_load_dwordx4 v[48:51], v[56:57], off
	ds_read_b128 v[52:55], v145 offset:24576
	ds_read_b128 v[56:59], v168 offset:24576
	s_waitcnt lgkmcnt(1)
	v_mfma_f32_16x16x32_bf16 v[44:47], v[52:55], v[104:107], v[44:47]
	ds_read_b128 v[136:139], v145 offset:26624
	ds_read_b128 v[140:143], v168 offset:26624
	s_waitcnt lgkmcnt(2)
	v_mfma_f32_16x16x32_bf16 v[44:47], v[56:59], v[112:115], v[44:47]
	s_waitcnt lgkmcnt(1)
	v_mfma_f32_16x16x32_bf16 v[40:43], v[136:139], v[104:107], v[40:43]
	s_waitcnt vmcnt(0)
	s_nop 4
	v_pk_mul_f32 v[46:47], v[46:47], v[50:51]
	v_pk_mul_f32 v[44:45], v[44:45], v[48:49]
	global_store_dwordx4 v[154:155], v[44:47], off offset:256
	global_load_dwordx4 v[44:47], v[146:147], off
	s_waitcnt lgkmcnt(0)
	v_mfma_f32_16x16x32_bf16 v[40:43], v[140:143], v[112:115], v[40:43]
	ds_read_b128 v[48:51], v145 offset:28672
	ds_read_b128 v[146:149], v145 offset:30720
	s_waitcnt lgkmcnt(1)
	v_mfma_f32_16x16x32_bf16 v[36:39], v[48:51], v[104:107], v[36:39]
	s_waitcnt vmcnt(0)
	s_nop 2
	v_pk_mul_f32 v[42:43], v[42:43], v[46:47]
	v_pk_mul_f32 v[40:41], v[40:41], v[44:45]
	global_store_dwordx4 v[154:155], v[40:43], off offset:272
	global_load_dwordx4 v[40:43], v[166:167], off
	ds_read_b128 v[44:47], v168 offset:28672
	s_waitcnt lgkmcnt(1)
	v_mfma_f32_16x16x32_bf16 v[32:35], v[146:149], v[104:107], v[32:35]
	ds_read_b128 v[104:107], v168 offset:30720
	v_mov_b32_e32 v167, v73
	v_or_b32_e32 v166, 0x190, v72
	s_waitcnt lgkmcnt(1)
	v_mfma_f32_16x16x32_bf16 v[36:39], v[44:47], v[112:115], v[36:39]
	v_lshl_add_u64 v[116:117], v[150:151], 0, v[166:167]
	s_waitcnt vmcnt(0)
	s_nop 5
	v_pk_mul_f32 v[38:39], v[38:39], v[42:43]
	v_pk_mul_f32 v[36:37], v[36:37], v[40:41]
	global_store_dwordx4 v[154:155], v[36:39], off offset:384
	global_load_dwordx4 v[36:39], v[116:117], off
	v_mul_hi_i32 v40, v99, s39
	v_lshrrev_b32_e32 v41, 31, v40
	v_ashrrev_i32_e32 v40, 11, v40
	v_add_u32_e32 v40, v40, v41
	v_mad_i32_i24 v41, v40, s40, v99
	v_cmp_lt_i32_e32 vcc, s41, v41
	s_waitcnt lgkmcnt(0)
	v_mfma_f32_16x16x32_bf16 v[32:35], v[104:107], v[112:115], v[32:35]
	v_cndmask_b32_e32 v40, 2, v40, vcc
	v_mul_hi_i32_i24_e32 v41, 0x6000, v40
	v_mul_i32_i24_e32 v40, 0x6000, v40
	v_lshl_add_u64 v[40:41], s[94:95], 0, v[40:41]
	v_lshl_add_u64 v[40:41], v[40:41], 0, s[34:35]
	v_lshl_add_u64 v[42:43], v[40:41], 0, v[72:73]
	v_mfma_f32_16x16x32_bf16 v[16:19], v[100:103], v[64:67], v[16:19]
	s_waitcnt vmcnt(0)
	v_pk_mul_f32 v[34:35], v[34:35], v[38:39]
	v_pk_mul_f32 v[32:33], v[32:33], v[36:37]
	global_store_dwordx4 v[154:155], v[32:35], off offset:400
	global_load_dwordx4 v[32:35], v[42:43], off
	v_mul_hi_i32 v36, v99, s38
	v_lshrrev_b32_e32 v37, 31, v36
	v_lshrrev_b32_e32 v36, 11, v36
	v_add_u32_e32 v36, v36, v37
	v_lshl_add_u32 v36, v36, 13, v99
	v_ashrrev_i32_e32 v37, 31, v36
	v_lshl_add_u64 v[36:37], v[36:37], 0, s[8:9]
	v_lshlrev_b64 v[36:37], 12, v[36:37]
	v_lshl_add_u64 v[36:37], s[6:7], 0, v[36:37]
	v_lshl_add_u64 v[36:37], v[36:37], 0, v[72:73]
	v_lshl_add_u64 v[38:39], v[40:41], 0, v[152:153]
	v_mfma_f32_16x16x32_bf16 v[12:15], v[128:131], v[108:111], v[12:15]
	s_waitcnt vmcnt(0)
	v_pk_mul_f32 v[30:31], v[30:31], v[34:35]
	v_pk_mul_f32 v[28:29], v[28:29], v[32:33]
	global_store_dwordx4 v[36:37], v[28:31], off
	global_load_dwordx4 v[28:31], v[38:39], off
	v_lshl_add_u64 v[32:33], v[40:41], 0, v[156:157]
	v_mfma_f32_16x16x32_bf16 v[12:15], v[132:135], v[64:67], v[12:15]
	s_waitcnt vmcnt(0)
	v_pk_mul_f32 v[26:27], v[26:27], v[30:31]
	v_pk_mul_f32 v[24:25], v[24:25], v[28:29]
	global_store_dwordx4 v[36:37], v[24:27], off offset:16
	global_load_dwordx4 v[24:27], v[32:33], off
	v_lshl_add_u64 v[28:29], v[40:41], 0, v[158:159]
	v_mfma_f32_16x16x32_bf16 v[8:11], v[52:55], v[108:111], v[8:11]
	s_waitcnt vmcnt(0)
	v_pk_mul_f32 v[18:19], v[18:19], v[26:27]
	v_pk_mul_f32 v[16:17], v[16:17], v[24:25]
	global_store_dwordx4 v[36:37], v[16:19], off offset:128
	global_load_dwordx4 v[16:19], v[28:29], off
	v_lshl_add_u64 v[24:25], v[40:41], 0, v[160:161]
	v_mfma_f32_16x16x32_bf16 v[8:11], v[56:59], v[64:67], v[8:11]
	s_waitcnt vmcnt(0)
	v_pk_mul_f32 v[14:15], v[14:15], v[18:19]
	v_pk_mul_f32 v[12:13], v[12:13], v[16:17]
	global_store_dwordx4 v[36:37], v[12:15], off offset:144
	global_load_dwordx4 v[12:15], v[24:25], off
	v_lshl_add_u64 v[16:17], v[40:41], 0, v[162:163]
	v_mfma_f32_16x16x32_bf16 v[4:7], v[136:139], v[108:111], v[4:7]
	s_waitcnt vmcnt(0)
	v_pk_mul_f32 v[10:11], v[10:11], v[14:15]
	v_pk_mul_f32 v[8:9], v[8:9], v[12:13]
	global_store_dwordx4 v[36:37], v[8:11], off offset:256
	global_load_dwordx4 v[8:11], v[16:17], off
	v_mfma_f32_16x16x32_bf16 v[4:7], v[140:143], v[64:67], v[4:7]
	v_lshl_add_u64 v[12:13], v[40:41], 0, v[164:165]
	v_mfma_f32_16x16x32_bf16 v[0:3], v[48:51], v[108:111], v[0:3]
	v_mfma_f32_16x16x32_bf16 v[0:3], v[44:47], v[64:67], v[0:3]
	s_waitcnt vmcnt(0)
	s_nop 3
	v_pk_mul_f32 v[6:7], v[6:7], v[10:11]
	v_pk_mul_f32 v[4:5], v[4:5], v[8:9]
	global_store_dwordx4 v[36:37], v[4:7], off offset:272
	global_load_dwordx4 v[4:7], v[12:13], off
	v_lshl_add_u64 v[8:9], v[40:41], 0, v[166:167]
	v_mfma_f32_16x16x32_bf16 v[20:23], v[146:149], v[108:111], v[20:23]
	s_waitcnt vmcnt(0)
	v_pk_mul_f32 v[2:3], v[2:3], v[6:7]
	v_pk_mul_f32 v[0:1], v[0:1], v[4:5]
	global_store_dwordx4 v[36:37], v[0:3], off offset:384
	global_load_dwordx4 v[0:3], v[8:9], off
	v_mfma_f32_16x16x32_bf16 v[4:7], v[104:107], v[64:67], v[20:23]
	s_waitcnt vmcnt(0)
	s_nop 6
	v_pk_mul_f32 v[2:3], v[6:7], v[2:3]
	v_pk_mul_f32 v[0:1], v[4:5], v[0:1]
	global_store_dwordx4 v[36:37], v[0:3], off offset:400
	s_cbranch_scc0 .LBB0_1090

.LBB0_1217:
	s_add_i32 s41, s3, 0x8000
	s_and_b32 s40, s41, 0x8000
	s_add_i32 s40, s40, 0
	s_add_u32 s86, s40, s87
	s_mov_b32 m0, s86
	s_waitcnt vmcnt(0) lgkmcnt(0)
	s_barrier
	global_load_lds_dwordx4 v244, s[96:97]
	s_add_u32 m0, s86, 0x1000
	s_nop 0
	global_load_lds_dwordx4 v246, s[96:97]
	s_add_u32 m0, s86, 0x2000
	s_nop 0
	global_load_lds_dwordx4 v248, s[96:97]
	s_add_u32 m0, s86, 0x3000
	s_nop 0
	global_load_lds_dwordx4 v250, s[96:97]
	s_add_u32 m0, s86, 0x4000
	s_nop 0
	global_load_lds_dwordx4 v245, s[88:89]
	s_add_u32 m0, s86, 0x5000
	s_nop 0
	global_load_lds_dwordx4 v247, s[88:89]
	s_add_u32 m0, s86, 0x6000
	s_nop 0
	global_load_lds_dwordx4 v249, s[88:89]
	s_add_u32 m0, s86, 0x7000
	s_nop 0
	global_load_lds_dwordx4 v251, s[88:89]
	s_add_u32 s96, s96, 0x80
	s_addc_u32 s97, s97, 0
	s_add_u32 s88, s88, 0x80
	s_addc_u32 s89, s89, 0
	s_and_b32 s3, s3, 0x8000
	s_add_i32 s3, s3, 0
	v_add3_u32 v145, s3, v87, v88
	v_add3_u32 v186, s3, v88, v89
	v_add3_u32 v187, s3, v87, v90
	v_add3_u32 v188, s3, v89, v90
	ds_read_b128 v[112:115], v186
	ds_read_b128 v[104:107], v145 offset:16384
	ds_read_b128 v[108:111], v145 offset:18432
	ds_read_b128 v[116:119], v186 offset:2048
	ds_read_b128 v[120:123], v145 offset:20480
	ds_read_b128 v[124:127], v145 offset:22528
	ds_read_b128 v[128:131], v145 offset:24576
	ds_read_b128 v[132:135], v145 offset:26624
	ds_read_b128 v[136:139], v145 offset:28672
	ds_read_b128 v[140:143], v145 offset:30720
	ds_read_b128 v[154:157], v188
	ds_read_b128 v[146:149], v187 offset:16384
	ds_read_b128 v[150:153], v187 offset:18432
	ds_read_b128 v[158:161], v188 offset:2048
	ds_read_b128 v[162:165], v187 offset:20480
	ds_read_b128 v[166:169], v187 offset:22528
	ds_read_b128 v[170:173], v187 offset:24576
	ds_read_b128 v[174:177], v187 offset:26624
	ds_read_b128 v[178:181], v187 offset:28672
	ds_read_b128 v[182:185], v187 offset:30720
	s_add_u32 s0, s0, 0x80
	s_addc_u32 s1, s1, 0
	s_cmpk_eq_i32 s0, 0x780
	s_mov_b32 s3, s41
	s_waitcnt lgkmcnt(15)
	v_mfma_f32_16x16x32_bf16 v[60:63], v[104:107], v[112:115], v[60:63]
	v_mfma_f32_16x16x32_bf16 v[56:59], v[108:111], v[112:115], v[56:59]
	v_mfma_f32_16x16x32_bf16 v[24:27], v[104:107], v[116:119], v[24:27]
	v_mfma_f32_16x16x32_bf16 v[20:23], v[108:111], v[116:119], v[20:23]
	v_mfma_f32_16x16x32_bf16 v[52:55], v[120:123], v[112:115], v[52:55]
	v_mfma_f32_16x16x32_bf16 v[16:19], v[120:123], v[116:119], v[16:19]
	s_waitcnt lgkmcnt(14)
	v_mfma_f32_16x16x32_bf16 v[48:51], v[124:127], v[112:115], v[48:51]
	v_mfma_f32_16x16x32_bf16 v[12:15], v[124:127], v[116:119], v[12:15]
	s_waitcnt lgkmcnt(13)
	v_mfma_f32_16x16x32_bf16 v[44:47], v[128:131], v[112:115], v[44:47]
	v_mfma_f32_16x16x32_bf16 v[8:11], v[128:131], v[116:119], v[8:11]
	s_waitcnt lgkmcnt(12)
	v_mfma_f32_16x16x32_bf16 v[36:39], v[132:135], v[112:115], v[36:39]
	v_mfma_f32_16x16x32_bf16 v[4:7], v[132:135], v[116:119], v[4:7]
	s_waitcnt lgkmcnt(11)
	v_mfma_f32_16x16x32_bf16 v[32:35], v[136:139], v[112:115], v[32:35]
	v_mfma_f32_16x16x32_bf16 v[0:3], v[136:139], v[116:119], v[0:3]
	s_waitcnt lgkmcnt(10)
	v_mfma_f32_16x16x32_bf16 v[28:31], v[140:143], v[112:115], v[28:31]
	v_mfma_f32_16x16x32_bf16 v[40:43], v[140:143], v[116:119], v[40:43]
	s_waitcnt lgkmcnt(8)
	v_mfma_f32_16x16x32_bf16 v[60:63], v[146:149], v[154:157], v[60:63]
	s_waitcnt lgkmcnt(7)
	v_mfma_f32_16x16x32_bf16 v[56:59], v[150:153], v[154:157], v[56:59]
	s_waitcnt lgkmcnt(6)
	v_mfma_f32_16x16x32_bf16 v[24:27], v[146:149], v[158:161], v[24:27]
	v_mfma_f32_16x16x32_bf16 v[20:23], v[150:153], v[158:161], v[20:23]
	s_waitcnt lgkmcnt(5)
	v_mfma_f32_16x16x32_bf16 v[52:55], v[162:165], v[154:157], v[52:55]
	v_mfma_f32_16x16x32_bf16 v[16:19], v[162:165], v[158:161], v[16:19]
	s_waitcnt lgkmcnt(4)
	v_mfma_f32_16x16x32_bf16 v[48:51], v[166:169], v[154:157], v[48:51]
	v_mfma_f32_16x16x32_bf16 v[12:15], v[166:169], v[158:161], v[12:15]
	s_waitcnt lgkmcnt(3)
	v_mfma_f32_16x16x32_bf16 v[44:47], v[170:173], v[154:157], v[44:47]
	v_mfma_f32_16x16x32_bf16 v[8:11], v[170:173], v[158:161], v[8:11]
	s_waitcnt lgkmcnt(2)
	v_mfma_f32_16x16x32_bf16 v[36:39], v[174:177], v[154:157], v[36:39]
	v_mfma_f32_16x16x32_bf16 v[4:7], v[174:177], v[158:161], v[4:7]
	s_waitcnt lgkmcnt(1)
	v_mfma_f32_16x16x32_bf16 v[32:35], v[178:181], v[154:157], v[32:35]
	v_mfma_f32_16x16x32_bf16 v[0:3], v[178:181], v[158:161], v[0:3]
	s_waitcnt lgkmcnt(0)
	v_mfma_f32_16x16x32_bf16 v[28:31], v[182:185], v[154:157], v[28:31]
	v_mfma_f32_16x16x32_bf16 v[40:43], v[182:185], v[158:161], v[40:43]
	s_cbranch_scc0 .LBB0_1217
	v_add_u32_e32 v64, s40, v87
	v_add_u32_e32 v103, v64, v88
	v_add3_u32 v112, s40, v88, v89
	s_waitcnt vmcnt(0)
	s_barrier
	ds_read_b128 v[82:85], v103 offset:16384
	ds_read_b128 v[104:107], v103 offset:18432
	ds_read_b128 v[108:111], v112
	ds_read_b128 v[112:115], v112 offset:2048
	ds_read_b128 v[116:119], v103 offset:20480
	ds_read_b128 v[120:123], v103 offset:22528
	ds_read_b128 v[124:127], v103 offset:24576
	ds_read_b128 v[128:131], v103 offset:26624
	ds_read_b128 v[132:135], v103 offset:28672
	ds_read_b128 v[136:139], v103 offset:30720
	v_add_u32_e32 v64, v64, v90
	s_waitcnt lgkmcnt(7)
	v_mfma_f32_16x16x32_bf16 v[60:63], v[82:85], v[108:111], v[60:63]
	s_mul_hi_i32 s0, s2, 0x3e0f83e1
	s_lshr_b32 s1, s0, 31
	s_ashr_i32 s56, s0, 4
	v_mfma_f32_16x16x32_bf16 v[56:59], v[104:107], v[108:111], v[56:59]
	s_add_i32 s56, s56, s1
	s_cmp_gt_i32 s39, 11
	s_cselect_b64 s[0:1], -1, 0
	s_waitcnt lgkmcnt(4)
	v_mfma_f32_16x16x32_bf16 v[48:51], v[120:123], v[108:111], v[48:51]
	s_lshl_b32 s53, s2, 7
	s_cmp_lt_i32 s39, 12
	s_mul_i32 s54, s56, 0xffffdf00
	s_waitcnt lgkmcnt(3)
	v_mfma_f32_16x16x32_bf16 v[44:47], v[124:127], v[108:111], v[44:47]
	s_waitcnt lgkmcnt(2)
	v_mfma_f32_16x16x32_bf16 v[36:39], v[128:131], v[108:111], v[36:39]
	s_waitcnt lgkmcnt(1)
	v_mfma_f32_16x16x32_bf16 v[32:35], v[132:135], v[108:111], v[32:35]
	s_waitcnt lgkmcnt(0)
	v_mfma_f32_16x16x32_bf16 v[28:31], v[136:139], v[108:111], v[28:31]
	v_mfma_f32_16x16x32_bf16 v[24:27], v[82:85], v[112:115], v[24:27]
	ds_read_b128 v[82:85], v64 offset:16384
	v_mfma_f32_16x16x32_bf16 v[52:55], v[116:119], v[108:111], v[52:55]
	v_mfma_f32_16x16x32_bf16 v[20:23], v[104:107], v[112:115], v[20:23]
	v_mfma_f32_16x16x32_bf16 v[16:19], v[116:119], v[112:115], v[16:19]
	v_mfma_f32_16x16x32_bf16 v[12:15], v[120:123], v[112:115], v[12:15]
	v_mfma_f32_16x16x32_bf16 v[8:11], v[124:127], v[112:115], v[8:11]
	v_mfma_f32_16x16x32_bf16 v[4:7], v[128:131], v[112:115], v[4:7]
	v_mfma_f32_16x16x32_bf16 v[0:3], v[132:135], v[112:115], v[0:3]
	v_mfma_f32_16x16x32_bf16 v[104:107], v[136:139], v[112:115], v[40:43]
	s_nop 2
	v_add3_u32 v40, s40, v90, v89
	ds_read_b128 v[108:111], v64 offset:18432
	ds_read_b128 v[112:115], v40
	ds_read_b128 v[116:119], v40 offset:2048
	ds_read_b128 v[120:123], v64 offset:20480
	ds_read_b128 v[124:127], v64 offset:22528
	ds_read_b128 v[128:131], v64 offset:24576
	ds_read_b128 v[132:135], v64 offset:26624
	ds_read_b128 v[136:139], v64 offset:28672
	ds_read_b128 v[140:143], v64 offset:30720
	s_waitcnt lgkmcnt(7)
	v_mfma_f32_16x16x32_bf16 v[60:63], v[82:85], v[112:115], v[60:63]
	v_mfma_f32_16x16x32_bf16 v[56:59], v[108:111], v[112:115], v[56:59]
	s_waitcnt lgkmcnt(5)
	v_mfma_f32_16x16x32_bf16 v[52:55], v[120:123], v[112:115], v[52:55]
	s_waitcnt lgkmcnt(4)
	v_mfma_f32_16x16x32_bf16 v[48:51], v[124:127], v[112:115], v[48:51]
	s_waitcnt lgkmcnt(3)
	v_mfma_f32_16x16x32_bf16 v[44:47], v[128:131], v[112:115], v[44:47]
	s_waitcnt lgkmcnt(2)
	v_mfma_f32_16x16x32_bf16 v[40:43], v[132:135], v[112:115], v[36:39]
	s_waitcnt lgkmcnt(1)
	v_mfma_f32_16x16x32_bf16 v[36:39], v[136:139], v[112:115], v[32:35]
	s_waitcnt lgkmcnt(0)
	v_mfma_f32_16x16x32_bf16 v[32:35], v[140:143], v[112:115], v[28:31]
	v_mfma_f32_16x16x32_bf16 v[28:31], v[82:85], v[116:119], v[24:27]
	v_mfma_f32_16x16x32_bf16 v[24:27], v[108:111], v[116:119], v[20:23]
	v_mfma_f32_16x16x32_bf16 v[20:23], v[120:123], v[116:119], v[16:19]
	v_mfma_f32_16x16x32_bf16 v[16:19], v[124:127], v[116:119], v[12:15]
	v_mfma_f32_16x16x32_bf16 v[12:15], v[128:131], v[116:119], v[8:11]
	v_mfma_f32_16x16x32_bf16 v[8:11], v[132:135], v[116:119], v[4:7]
	v_mfma_f32_16x16x32_bf16 v[4:7], v[136:139], v[116:119], v[0:3]
	v_mfma_f32_16x16x32_bf16 v[0:3], v[140:143], v[116:119], v[104:107]
	s_cbranch_scc0 .LBB0_1224
	s_add_i32 s40, s54, s53
	v_add_u32_e32 v64, s40, v70
	v_cmp_lt_i32_e32 vcc, s48, v64
	s_and_saveexec_b64 s[2:3], vcc
	s_cbranch_execz .LBB0_1221
	v_lshl_add_u32 v64, v64, 5, v102
	v_lshlrev_b64 v[108:109], 2, v[64:65]
	v_lshl_add_u64 v[104:105], v[76:77], 0, v[108:109]
	global_load_dwordx4 v[82:85], v[104:105], off
	s_nop 0
	global_load_dwordx4 v[104:107], v[104:105], off offset:16
	v_lshl_add_u64 v[112:113], v[74:75], 0, v[108:109]
	global_load_dwordx4 v[108:111], v[112:113], off
	s_nop 0
	global_load_dwordx4 v[112:115], v[112:113], off offset:16
	s_waitcnt vmcnt(3)
	v_pk_mul_f32 v[116:117], v[54:55], v[84:85]
	v_pk_mul_f32 v[118:119], v[52:53], v[82:83]
	v_pk_mul_f32 v[120:121], v[62:63], v[84:85]
	v_pk_mul_f32 v[122:123], v[60:61], v[82:83]
	s_waitcnt vmcnt(2)
	v_pk_mul_f32 v[124:125], v[50:51], v[106:107]
	v_pk_mul_f32 v[126:127], v[48:49], v[104:105]
	v_pk_mul_f32 v[128:129], v[58:59], v[106:107]
	v_pk_mul_f32 v[130:131], v[56:57], v[104:105]
	v_pk_mul_f32 v[132:133], v[38:39], v[84:85]
	v_pk_mul_f32 v[134:135], v[36:37], v[82:83]
	v_pk_mul_f32 v[84:85], v[46:47], v[84:85]
	v_pk_mul_f32 v[82:83], v[44:45], v[82:83]
	v_pk_mul_f32 v[136:137], v[34:35], v[106:107]
	v_pk_mul_f32 v[138:139], v[32:33], v[104:105]
	v_pk_mul_f32 v[106:107], v[42:43], v[106:107]
	v_pk_mul_f32 v[104:105], v[40:41], v[104:105]
	s_waitcnt vmcnt(1)
	v_pk_fma_f32 v[62:63], v[62:63], v[110:111], v[116:117] neg_lo:[0,0,1] neg_hi:[0,0,1]
	v_pk_fma_f32 v[60:61], v[60:61], v[108:109], v[118:119] neg_lo:[0,0,1] neg_hi:[0,0,1]
	v_pk_fma_f32 v[54:55], v[54:55], v[110:111], v[120:121]
	v_pk_fma_f32 v[52:53], v[52:53], v[108:109], v[122:123]
	s_waitcnt vmcnt(0)
	v_pk_fma_f32 v[58:59], v[58:59], v[114:115], v[124:125] neg_lo:[0,0,1] neg_hi:[0,0,1]
	v_pk_fma_f32 v[56:57], v[56:57], v[112:113], v[126:127] neg_lo:[0,0,1] neg_hi:[0,0,1]
	v_pk_fma_f32 v[50:51], v[50:51], v[114:115], v[128:129]
	v_pk_fma_f32 v[48:49], v[48:49], v[112:113], v[130:131]
	v_pk_fma_f32 v[46:47], v[46:47], v[110:111], v[132:133] neg_lo:[0,0,1] neg_hi:[0,0,1]
	v_pk_fma_f32 v[44:45], v[44:45], v[108:109], v[134:135] neg_lo:[0,0,1] neg_hi:[0,0,1]
	v_pk_fma_f32 v[38:39], v[38:39], v[110:111], v[84:85]
	v_pk_fma_f32 v[36:37], v[36:37], v[108:109], v[82:83]
	v_pk_fma_f32 v[42:43], v[42:43], v[114:115], v[136:137] neg_lo:[0,0,1] neg_hi:[0,0,1]
	v_pk_fma_f32 v[40:41], v[40:41], v[112:113], v[138:139] neg_lo:[0,0,1] neg_hi:[0,0,1]
	v_pk_fma_f32 v[34:35], v[34:35], v[114:115], v[106:107]
	v_pk_fma_f32 v[32:33], v[32:33], v[112:113], v[104:105]

.LBB0_1615:
	s_add_i32 s41, s39, 0x8000
	s_and_b32 s40, s41, 0x8000
	s_add_i32 s40, s40, 0
	s_add_u32 s86, s40, s87
	s_mov_b32 m0, s86
	s_waitcnt vmcnt(0) lgkmcnt(0)
	s_barrier
	global_load_lds_dwordx4 v244, s[96:97]
	s_add_u32 m0, s86, 0x1000
	s_nop 0
	global_load_lds_dwordx4 v246, s[96:97]
	s_add_u32 m0, s86, 0x2000
	s_nop 0
	global_load_lds_dwordx4 v248, s[96:97]
	s_add_u32 m0, s86, 0x3000
	s_nop 0
	global_load_lds_dwordx4 v250, s[96:97]
	s_add_u32 m0, s86, 0x4000
	s_nop 0
	global_load_lds_dwordx4 v245, s[88:89]
	s_add_u32 m0, s86, 0x5000
	s_nop 0
	global_load_lds_dwordx4 v247, s[88:89]
	s_add_u32 m0, s86, 0x6000
	s_nop 0
	global_load_lds_dwordx4 v249, s[88:89]
	s_add_u32 m0, s86, 0x7000
	s_nop 0
	global_load_lds_dwordx4 v251, s[88:89]
	s_add_u32 s96, s96, 0x80
	s_addc_u32 s97, s97, 0
	s_add_u32 s88, s88, 0x80
	s_addc_u32 s89, s89, 0
	s_and_b32 s39, s39, 0x8000
	s_add_i32 s39, s39, 0
	v_add3_u32 v145, s39, v84, v85
	v_add3_u32 v178, s39, v85, v86
	v_add3_u32 v179, s39, v84, v87
	v_add3_u32 v180, s39, v86, v87
	ds_read_b128 v[104:107], v178
	ds_read_b128 v[76:79], v145 offset:16384
	ds_read_b128 v[100:103], v145 offset:18432
	ds_read_b128 v[108:111], v178 offset:2048
	ds_read_b128 v[112:115], v145 offset:20480
	ds_read_b128 v[116:119], v145 offset:22528
	ds_read_b128 v[120:123], v145 offset:24576
	ds_read_b128 v[124:127], v145 offset:26624
	ds_read_b128 v[128:131], v145 offset:28672
	ds_read_b128 v[132:135], v145 offset:30720
	ds_read_b128 v[146:149], v180
	ds_read_b128 v[136:139], v179 offset:16384
	ds_read_b128 v[140:143], v179 offset:18432
	ds_read_b128 v[150:153], v180 offset:2048
	ds_read_b128 v[154:157], v179 offset:20480
	ds_read_b128 v[158:161], v179 offset:22528
	ds_read_b128 v[162:165], v179 offset:24576
	ds_read_b128 v[166:169], v179 offset:26624
	ds_read_b128 v[170:173], v179 offset:28672
	ds_read_b128 v[174:177], v179 offset:30720
	s_add_u32 s28, s28, 0x80
	s_addc_u32 s29, s29, 0
	s_cmpk_eq_i32 s28, 0x780
	s_mov_b32 s39, s41
	s_waitcnt lgkmcnt(15)
	v_mfma_f32_16x16x32_bf16 v[60:63], v[76:79], v[104:107], v[60:63]
	v_mfma_f32_16x16x32_bf16 v[56:59], v[100:103], v[104:107], v[56:59]
	v_mfma_f32_16x16x32_bf16 v[24:27], v[76:79], v[108:111], v[24:27]
	v_mfma_f32_16x16x32_bf16 v[20:23], v[100:103], v[108:111], v[20:23]
	v_mfma_f32_16x16x32_bf16 v[52:55], v[112:115], v[104:107], v[52:55]
	v_mfma_f32_16x16x32_bf16 v[16:19], v[112:115], v[108:111], v[16:19]
	s_waitcnt lgkmcnt(14)
	v_mfma_f32_16x16x32_bf16 v[48:51], v[116:119], v[104:107], v[48:51]
	v_mfma_f32_16x16x32_bf16 v[12:15], v[116:119], v[108:111], v[12:15]
	s_waitcnt lgkmcnt(13)
	v_mfma_f32_16x16x32_bf16 v[44:47], v[120:123], v[104:107], v[44:47]
	v_mfma_f32_16x16x32_bf16 v[8:11], v[120:123], v[108:111], v[8:11]
	s_waitcnt lgkmcnt(12)
	v_mfma_f32_16x16x32_bf16 v[40:43], v[124:127], v[104:107], v[40:43]
	v_mfma_f32_16x16x32_bf16 v[4:7], v[124:127], v[108:111], v[4:7]
	s_waitcnt lgkmcnt(11)
	v_mfma_f32_16x16x32_bf16 v[32:35], v[128:131], v[104:107], v[32:35]
	v_mfma_f32_16x16x32_bf16 v[0:3], v[128:131], v[108:111], v[0:3]
	s_waitcnt lgkmcnt(10)
	v_mfma_f32_16x16x32_bf16 v[28:31], v[132:135], v[104:107], v[28:31]
	v_mfma_f32_16x16x32_bf16 v[36:39], v[132:135], v[108:111], v[36:39]
	s_waitcnt lgkmcnt(8)
	v_mfma_f32_16x16x32_bf16 v[60:63], v[136:139], v[146:149], v[60:63]
	s_waitcnt lgkmcnt(7)
	v_mfma_f32_16x16x32_bf16 v[56:59], v[140:143], v[146:149], v[56:59]
	s_waitcnt lgkmcnt(6)
	v_mfma_f32_16x16x32_bf16 v[24:27], v[136:139], v[150:153], v[24:27]
	v_mfma_f32_16x16x32_bf16 v[20:23], v[140:143], v[150:153], v[20:23]
	s_waitcnt lgkmcnt(5)
	v_mfma_f32_16x16x32_bf16 v[52:55], v[154:157], v[146:149], v[52:55]
	v_mfma_f32_16x16x32_bf16 v[16:19], v[154:157], v[150:153], v[16:19]
	s_waitcnt lgkmcnt(4)
	v_mfma_f32_16x16x32_bf16 v[48:51], v[158:161], v[146:149], v[48:51]
	v_mfma_f32_16x16x32_bf16 v[12:15], v[158:161], v[150:153], v[12:15]
	s_waitcnt lgkmcnt(3)
	v_mfma_f32_16x16x32_bf16 v[44:47], v[162:165], v[146:149], v[44:47]
	v_mfma_f32_16x16x32_bf16 v[8:11], v[162:165], v[150:153], v[8:11]
	s_waitcnt lgkmcnt(2)
	v_mfma_f32_16x16x32_bf16 v[40:43], v[166:169], v[146:149], v[40:43]
	v_mfma_f32_16x16x32_bf16 v[4:7], v[166:169], v[150:153], v[4:7]
	s_waitcnt lgkmcnt(1)
	v_mfma_f32_16x16x32_bf16 v[32:35], v[170:173], v[146:149], v[32:35]
	v_mfma_f32_16x16x32_bf16 v[0:3], v[170:173], v[150:153], v[0:3]
	s_waitcnt lgkmcnt(0)
	v_mfma_f32_16x16x32_bf16 v[28:31], v[174:177], v[146:149], v[28:31]
	v_mfma_f32_16x16x32_bf16 v[36:39], v[174:177], v[150:153], v[36:39]
	s_cbranch_scc0 .LBB0_1615
	v_add_u32_e32 v80, s40, v84
	v_add_u32_e32 v81, v80, v85
	s_waitcnt vmcnt(0)
	s_barrier
	ds_read_b128 v[72:75], v81 offset:16384
	v_add3_u32 v99, s40, v85, v86
	ds_read_b128 v[76:79], v81 offset:18432
	ds_read_b128 v[100:103], v99
	ds_read_b128 v[104:107], v99 offset:2048
	ds_read_b128 v[108:111], v81 offset:20480
	ds_read_b128 v[112:115], v81 offset:22528
	ds_read_b128 v[116:119], v81 offset:24576
	ds_read_b128 v[120:123], v81 offset:26624
	ds_read_b128 v[124:127], v81 offset:28672
	ds_read_b128 v[128:131], v81 offset:30720
	v_add_u32_e32 v80, v80, v87
	s_waitcnt lgkmcnt(7)
	v_mfma_f32_16x16x32_bf16 v[60:63], v[72:75], v[100:103], v[60:63]
	s_lshl_b32 s38, s38, 7
	v_mfma_f32_16x16x32_bf16 v[56:59], v[76:79], v[100:103], v[56:59]
	s_waitcnt lgkmcnt(4)
	v_mfma_f32_16x16x32_bf16 v[48:51], v[112:115], v[100:103], v[48:51]
	s_waitcnt lgkmcnt(3)
	v_mfma_f32_16x16x32_bf16 v[44:47], v[116:119], v[100:103], v[44:47]
	s_waitcnt lgkmcnt(2)
	v_mfma_f32_16x16x32_bf16 v[40:43], v[120:123], v[100:103], v[40:43]
	s_waitcnt lgkmcnt(1)
	v_mfma_f32_16x16x32_bf16 v[32:35], v[124:127], v[100:103], v[32:35]
	s_waitcnt lgkmcnt(0)
	v_mfma_f32_16x16x32_bf16 v[28:31], v[128:131], v[100:103], v[28:31]
	v_mfma_f32_16x16x32_bf16 v[24:27], v[72:75], v[104:107], v[24:27]
	ds_read_b128 v[72:75], v80 offset:16384
	v_mfma_f32_16x16x32_bf16 v[52:55], v[108:111], v[100:103], v[52:55]
	v_mfma_f32_16x16x32_bf16 v[20:23], v[76:79], v[104:107], v[20:23]
	v_mfma_f32_16x16x32_bf16 v[16:19], v[108:111], v[104:107], v[16:19]
	v_mfma_f32_16x16x32_bf16 v[12:15], v[112:115], v[104:107], v[12:15]
	v_mfma_f32_16x16x32_bf16 v[8:11], v[116:119], v[104:107], v[8:11]
	v_mfma_f32_16x16x32_bf16 v[4:7], v[120:123], v[104:107], v[4:7]
	v_mfma_f32_16x16x32_bf16 v[0:3], v[124:127], v[104:107], v[0:3]
	v_mfma_f32_16x16x32_bf16 v[100:103], v[128:131], v[104:107], v[36:39]
	s_nop 2
	v_add3_u32 v36, s40, v87, v86
	ds_read_b128 v[76:79], v80 offset:18432
	ds_read_b128 v[104:107], v36
	ds_read_b128 v[108:111], v36 offset:2048
	ds_read_b128 v[128:131], v80 offset:28672
	ds_read_b128 v[132:135], v80 offset:30720
	ds_read_b128 v[112:115], v80 offset:20480
	ds_read_b128 v[116:119], v80 offset:22528
	ds_read_b128 v[120:123], v80 offset:24576
	ds_read_b128 v[124:127], v80 offset:26624
	s_waitcnt lgkmcnt(7)
	v_mfma_f32_16x16x32_bf16 v[60:63], v[72:75], v[104:107], v[60:63]
	s_waitcnt lgkmcnt(5)
	v_mfma_f32_16x16x32_bf16 v[36:39], v[128:131], v[104:107], v[32:35]
	s_waitcnt lgkmcnt(4)
	v_mfma_f32_16x16x32_bf16 v[32:35], v[132:135], v[104:107], v[28:31]
	v_mfma_f32_16x16x32_bf16 v[28:31], v[72:75], v[108:111], v[24:27]
	v_add_u32_e32 v72, s38, v83
	v_mul_hi_i32 v73, v72, s31
	v_mfma_f32_16x16x32_bf16 v[24:27], v[76:79], v[108:111], v[20:23]
	s_waitcnt lgkmcnt(3)
	v_mfma_f32_16x16x32_bf16 v[20:23], v[112:115], v[108:111], v[16:19]
	s_waitcnt lgkmcnt(2)
	v_mfma_f32_16x16x32_bf16 v[16:19], v[116:119], v[108:111], v[12:15]
	s_waitcnt lgkmcnt(1)
	v_mfma_f32_16x16x32_bf16 v[12:15], v[120:123], v[108:111], v[8:11]
	s_waitcnt lgkmcnt(0)
	v_mfma_f32_16x16x32_bf16 v[8:11], v[124:127], v[108:111], v[4:7]
	s_nop 2
	v_lshrrev_b32_e32 v4, 31, v73
	v_ashrrev_i32_e32 v5, 11, v73
	v_mfma_f32_16x16x32_bf16 v[56:59], v[76:79], v[104:107], v[56:59]
	v_add_u32_e32 v73, v5, v4
	v_mad_i32_i24 v78, v73, s33, v72
	v_lshlrev_b32_e32 v75, 13, v73
	v_mfma_f32_16x16x32_bf16 v[52:55], v[112:115], v[104:107], v[52:55]
	v_cmp_lt_i32_e32 vcc, s34, v78
	v_add3_u32 v74, v75, v78, s35
	v_mfma_f32_16x16x32_bf16 v[48:51], v[116:119], v[104:107], v[48:51]
	v_mfma_f32_16x16x32_bf16 v[44:47], v[120:123], v[104:107], v[44:47]
	v_mfma_f32_16x16x32_bf16 v[40:43], v[124:127], v[104:107], v[40:43]
	v_mfma_f32_16x16x32_bf16 v[4:7], v[128:131], v[108:111], v[0:3]
	v_mfma_f32_16x16x32_bf16 v[0:3], v[132:135], v[108:111], v[100:103]
	s_and_saveexec_b64 s[28:29], vcc
	s_xor_b64 s[28:29], exec, s[28:29]
	v_add3_u32 v72, v75, v78, s35
	s_or_saveexec_b64 s[28:29], s[28:29]
	v_mov_b64_e32 v[76:77], s[92:93]
	v_lshl_add_u32 v75, v73, 8, v78
	s_xor_b64 exec, exec, s[28:29]
	v_lshl_add_u32 v72, v73, 8, v78
	v_mov_b64_e32 v[76:77], s[2:3]
	s_or_b64 exec, exec, s[28:29]
	s_and_saveexec_b64 s[28:29], vcc
	s_xor_b64 s[28:29], exec, s[28:29]
	s_cbranch_execz .LBB0_1622
	v_add_u32_e32 v73, 3, v73
	v_mul_hi_i32_i24_e32 v79, 0x6000, v73
	v_mul_i32_i24_e32 v78, 0x6000, v73
	s_or_saveexec_b64 s[28:29], s[28:29]
	v_mov_b64_e32 v[80:81], s[92:93]
	s_xor_b64 exec, exec, s[28:29]
	s_cbranch_execnz .LBB0_1623
	s_branch .LBB0_1624

.LBB0_1759:
	s_add_i32 s36, s34, 0x8000
	s_and_b32 s35, s36, 0x8000
	s_add_i32 s35, s35, 0
	s_add_u32 s86, s35, s87
	s_mov_b32 m0, s86
	s_waitcnt vmcnt(0) lgkmcnt(0)
	s_barrier
	global_load_lds_dwordx4 v244, s[96:97]
	s_add_u32 m0, s86, 0x1000
	s_nop 0
	global_load_lds_dwordx4 v246, s[96:97]
	s_add_u32 m0, s86, 0x2000
	s_nop 0
	global_load_lds_dwordx4 v248, s[96:97]
	s_add_u32 m0, s86, 0x3000
	s_nop 0
	global_load_lds_dwordx4 v250, s[96:97]
	s_add_u32 m0, s86, 0x4000
	s_nop 0
	global_load_lds_dwordx4 v245, s[88:89]
	s_add_u32 m0, s86, 0x5000
	s_nop 0
	global_load_lds_dwordx4 v247, s[88:89]
	s_add_u32 m0, s86, 0x6000
	s_nop 0
	global_load_lds_dwordx4 v249, s[88:89]
	s_add_u32 m0, s86, 0x7000
	s_nop 0
	global_load_lds_dwordx4 v251, s[88:89]
	s_add_u32 s96, s96, 0x80
	s_addc_u32 s97, s97, 0
	s_add_u32 s88, s88, 0x80
	s_addc_u32 s89, s89, 0
	s_and_b32 s34, s34, 0x8000
	s_add_i32 s34, s34, 0
	v_add3_u32 v143, s34, v80, v81
	v_add3_u32 v145, s34, v81, v82
	v_add3_u32 v206, s34, v80, v83
	v_add3_u32 v207, s34, v82, v83
	ds_read_b128 v[102:105], v145
	ds_read_b128 v[94:97], v143 offset:16384
	ds_read_b128 v[98:101], v143 offset:18432
	ds_read_b128 v[106:109], v145 offset:2048
	ds_read_b128 v[110:113], v143 offset:20480
	ds_read_b128 v[114:117], v143 offset:22528
	ds_read_b128 v[118:121], v143 offset:24576
	ds_read_b128 v[122:125], v143 offset:26624
	ds_read_b128 v[126:129], v143 offset:28672
	ds_read_b128 v[130:133], v143 offset:30720
	ds_read_b128 v[174:177], v207
	ds_read_b128 v[166:169], v206 offset:16384
	ds_read_b128 v[170:173], v206 offset:18432
	ds_read_b128 v[178:181], v207 offset:2048
	ds_read_b128 v[182:185], v206 offset:20480
	ds_read_b128 v[186:189], v206 offset:22528
	ds_read_b128 v[190:193], v206 offset:24576
	ds_read_b128 v[194:197], v206 offset:26624
	ds_read_b128 v[198:201], v206 offset:28672
	ds_read_b128 v[202:205], v206 offset:30720
	s_add_u32 s26, s26, 0x80
	s_addc_u32 s27, s27, 0
	s_cmpk_eq_i32 s26, 0x780
	s_mov_b32 s34, s36
	s_waitcnt lgkmcnt(15)
	v_mfma_f32_16x16x32_bf16 v[60:63], v[94:97], v[102:105], v[60:63]
	v_mfma_f32_16x16x32_bf16 v[56:59], v[98:101], v[102:105], v[56:59]
	v_mfma_f32_16x16x32_bf16 v[28:31], v[94:97], v[106:109], v[28:31]
	v_mfma_f32_16x16x32_bf16 v[24:27], v[98:101], v[106:109], v[24:27]
	v_mfma_f32_16x16x32_bf16 v[52:55], v[110:113], v[102:105], v[52:55]
	v_mfma_f32_16x16x32_bf16 v[20:23], v[110:113], v[106:109], v[20:23]
	s_waitcnt lgkmcnt(14)
	v_mfma_f32_16x16x32_bf16 v[48:51], v[114:117], v[102:105], v[48:51]
	v_mfma_f32_16x16x32_bf16 v[12:15], v[114:117], v[106:109], v[12:15]
	s_waitcnt lgkmcnt(13)
	v_mfma_f32_16x16x32_bf16 v[44:47], v[118:121], v[102:105], v[44:47]
	v_mfma_f32_16x16x32_bf16 v[8:11], v[118:121], v[106:109], v[8:11]
	s_waitcnt lgkmcnt(12)
	v_mfma_f32_16x16x32_bf16 v[40:43], v[122:125], v[102:105], v[40:43]
	v_mfma_f32_16x16x32_bf16 v[4:7], v[122:125], v[106:109], v[4:7]
	s_waitcnt lgkmcnt(11)
	v_mfma_f32_16x16x32_bf16 v[36:39], v[126:129], v[102:105], v[36:39]
	v_mfma_f32_16x16x32_bf16 v[0:3], v[126:129], v[106:109], v[0:3]
	s_waitcnt lgkmcnt(10)
	v_mfma_f32_16x16x32_bf16 v[32:35], v[130:133], v[102:105], v[32:35]
	v_mfma_f32_16x16x32_bf16 v[16:19], v[130:133], v[106:109], v[16:19]
	s_waitcnt lgkmcnt(8)
	v_mfma_f32_16x16x32_bf16 v[60:63], v[166:169], v[174:177], v[60:63]
	s_waitcnt lgkmcnt(7)
	v_mfma_f32_16x16x32_bf16 v[56:59], v[170:173], v[174:177], v[56:59]
	s_waitcnt lgkmcnt(6)
	v_mfma_f32_16x16x32_bf16 v[28:31], v[166:169], v[178:181], v[28:31]
	v_mfma_f32_16x16x32_bf16 v[24:27], v[170:173], v[178:181], v[24:27]
	s_waitcnt lgkmcnt(5)
	v_mfma_f32_16x16x32_bf16 v[52:55], v[182:185], v[174:177], v[52:55]
	v_mfma_f32_16x16x32_bf16 v[20:23], v[182:185], v[178:181], v[20:23]
	s_waitcnt lgkmcnt(4)
	v_mfma_f32_16x16x32_bf16 v[48:51], v[186:189], v[174:177], v[48:51]
	v_mfma_f32_16x16x32_bf16 v[12:15], v[186:189], v[178:181], v[12:15]
	s_waitcnt lgkmcnt(3)
	v_mfma_f32_16x16x32_bf16 v[44:47], v[190:193], v[174:177], v[44:47]
	v_mfma_f32_16x16x32_bf16 v[8:11], v[190:193], v[178:181], v[8:11]
	s_waitcnt lgkmcnt(2)
	v_mfma_f32_16x16x32_bf16 v[40:43], v[194:197], v[174:177], v[40:43]
	v_mfma_f32_16x16x32_bf16 v[4:7], v[194:197], v[178:181], v[4:7]
	s_waitcnt lgkmcnt(1)
	v_mfma_f32_16x16x32_bf16 v[36:39], v[198:201], v[174:177], v[36:39]
	v_mfma_f32_16x16x32_bf16 v[0:3], v[198:201], v[178:181], v[0:3]
	s_waitcnt lgkmcnt(0)
	v_mfma_f32_16x16x32_bf16 v[32:35], v[202:205], v[174:177], v[32:35]
	v_mfma_f32_16x16x32_bf16 v[16:19], v[202:205], v[178:181], v[16:19]
	s_cbranch_scc0 .LBB0_1759
	v_add_u32_e32 v138, s35, v80
	v_add_u32_e32 v126, v138, v81
	s_waitcnt vmcnt(0)
	s_barrier
	ds_read_b128 v[74:77], v126 offset:16384
	v_add3_u32 v102, s35, v81, v82
	ds_read_b128 v[94:97], v102
	ds_read_b128 v[98:101], v126 offset:18432
	ds_read_b128 v[102:105], v102 offset:2048
	ds_read_b128 v[106:109], v126 offset:20480
	ds_read_b128 v[110:113], v126 offset:22528
	ds_read_b128 v[114:117], v126 offset:24576
	ds_read_b128 v[118:121], v126 offset:26624
	v_add3_u32 v134, s35, v83, v82
	v_add_u32_e32 v142, v138, v83
	ds_read_b128 v[122:125], v126 offset:28672
	ds_read_b128 v[126:129], v126 offset:30720
	ds_read_b128 v[130:133], v134
	ds_read_b128 v[134:137], v134 offset:2048
	ds_read_b128 v[138:141], v142 offset:16384
	ds_read_b128 v[146:149], v142 offset:18432
	s_waitcnt lgkmcnt(11)
	v_mfma_f32_16x16x32_bf16 v[56:59], v[98:101], v[94:97], v[56:59]
	s_lshl_b32 s33, s33, 7
	s_lshl_b32 s26, s31, 7
	s_ashr_i32 s27, s26, 31
	v_mfma_f32_16x16x32_bf16 v[60:63], v[74:77], v[94:97], v[60:63]
	s_lshl_b64 s[26:27], s[26:27], 1
	s_add_i32 s30, s30, s28
	s_cmpk_gt_i32 s30, 0xfff
	s_waitcnt lgkmcnt(0)
	v_mfma_f32_16x16x32_bf16 v[56:59], v[146:149], v[130:133], v[56:59]
	v_mfma_f32_16x16x32_bf16 v[48:51], v[110:113], v[94:97], v[48:51]
	v_mfma_f32_16x16x32_bf16 v[52:55], v[106:109], v[94:97], v[52:55]
	s_nop 5
	v_max_f32_e32 v56, v56, v56
	v_max_f32_e32 v57, v57, v57
	v_max_f32_e32 v56, 0, v56
	v_mfma_f32_16x16x32_bf16 v[44:47], v[114:117], v[94:97], v[44:47]
	v_max_f32_e32 v57, 0, v57
	v_max_f32_e32 v59, v59, v59
	v_max_f32_e32 v59, 0, v59
	v_mfma_f32_16x16x32_bf16 v[40:43], v[118:121], v[94:97], v[40:43]
	v_mfma_f32_16x16x32_bf16 v[36:39], v[122:125], v[94:97], v[36:39]
	v_mfma_f32_16x16x32_bf16 v[32:35], v[126:129], v[94:97], v[32:35]
	ds_read_b128 v[94:97], v142 offset:20480
	ds_read_b128 v[150:153], v142 offset:22528
	ds_read_b128 v[154:157], v142 offset:24576
	ds_read_b128 v[158:161], v142 offset:26624
	v_mfma_f32_16x16x32_bf16 v[60:63], v[138:141], v[130:133], v[60:63]
	s_waitcnt lgkmcnt(2)
	v_mfma_f32_16x16x32_bf16 v[48:51], v[150:153], v[130:133], v[48:51]
	v_mfma_f32_16x16x32_bf16 v[20:23], v[106:109], v[102:105], v[20:23]
	v_mul_f32_e64 v106, v56, v56
	v_mul_f32_e64 v107, v57, v57
	v_max_f32_e32 v57, v58, v58
	s_nop 1
	v_max_f32_e32 v60, v60, v60
	v_mfma_f32_16x16x32_bf16 v[24:27], v[98:101], v[102:105], v[24:27]
	v_add_u32_e32 v100, s33, v79
	v_mov_b64_e32 v[98:99], s[0:1]
	v_max_f32_e32 v61, v61, v61
	v_max_f32_e32 v56, v62, v62
	v_max_f32_e32 v58, 0, v57
	v_max_f32_e32 v57, v63, v63
	v_mad_i64_i32 v[100:101], s[34:35], v100, s29, v[98:99]
	v_max_f32_e32 v60, 0, v60
	v_max_f32_e32 v61, 0, v61
	v_max_f32_e32 v56, 0, v56
	v_max_f32_e32 v57, 0, v57
	v_mfma_f32_16x16x32_bf16 v[52:55], v[94:97], v[130:133], v[52:55]
	v_lshl_add_u64 v[100:101], v[100:101], 0, s[26:27]
	v_pk_mul_f32 v[60:61], v[60:61], v[60:61]
	v_pk_mul_f32 v[62:63], v[56:57], v[56:57]
	v_mfma_f32_16x16x32_bf16 v[28:31], v[74:77], v[102:105], v[28:31]
	v_max_f32_e32 v48, v48, v48
	v_max_f32_e32 v49, v49, v49
	ds_read_b128 v[74:77], v142 offset:28672
	ds_read_b128 v[162:165], v142 offset:30720
	v_mfma_f32_16x16x32_bf16 v[12:15], v[110:113], v[102:105], v[12:15]
	v_lshl_add_u64 v[100:101], v[100:101], 0, v[64:65]
	v_cvt_pk_bf16_f32 v56, v60, v61
	v_cvt_pk_bf16_f32 v57, v62, v63
	v_mfma_f32_16x16x32_bf16 v[8:11], v[114:117], v[102:105], v[8:11]
	v_max_f32_e32 v48, 0, v48
	v_max_f32_e32 v49, 0, v49
	v_max_f32_e32 v52, v52, v52
	v_mfma_f32_16x16x32_bf16 v[4:7], v[118:121], v[102:105], v[4:7]
	v_max_f32_e32 v53, v53, v53
	v_max_f32_e32 v51, v51, v51
	v_max_f32_e32 v52, 0, v52
	v_mfma_f32_16x16x32_bf16 v[0:3], v[122:125], v[102:105], v[0:3]
	v_max_f32_e32 v53, 0, v53
	v_max_f32_e32 v51, 0, v51
	v_pk_mul_f32 v[52:53], v[52:53], v[52:53]
	v_mfma_f32_16x16x32_bf16 v[16:19], v[126:129], v[102:105], v[16:19]
	v_mul_f32_e64 v102, v58, v58
	v_mul_f32_e64 v103, v59, v59
	v_cvt_pk_bf16_f32 v58, v106, v107
	v_cvt_pk_bf16_f32 v59, v102, v103
	s_waitcnt lgkmcnt(2)
	v_mfma_f32_16x16x32_bf16 v[40:43], v[158:161], v[130:133], v[40:43]
	global_store_dwordx4 v[100:101], v[56:59], off
	s_nop 1
	v_pk_mul_f32 v[56:57], v[48:49], v[48:49]
	v_max_f32_e32 v49, v50, v50
	v_max_f32_e32 v48, v54, v54
	v_max_f32_e32 v50, 0, v49
	v_max_f32_e32 v49, v55, v55
	v_mfma_f32_16x16x32_bf16 v[44:47], v[154:157], v[130:133], v[44:47]
	v_max_f32_e32 v48, 0, v48
	v_max_f32_e32 v49, 0, v49
	v_pk_mul_f32 v[54:55], v[48:49], v[48:49]
	v_pk_mul_f32 v[58:59], v[50:51], v[50:51]
	v_max_f32_e32 v40, v40, v40
	v_max_f32_e32 v41, v41, v41
	s_waitcnt lgkmcnt(0)
	v_mfma_f32_16x16x32_bf16 v[32:35], v[162:165], v[130:133], v[32:35]
	v_cvt_pk_bf16_f32 v48, v52, v53
	v_cvt_pk_bf16_f32 v49, v54, v55
	v_cvt_pk_bf16_f32 v50, v56, v57
	v_cvt_pk_bf16_f32 v51, v58, v59
	v_max_f32_e32 v40, 0, v40
	v_max_f32_e32 v41, 0, v41
	global_store_dwordx4 v[100:101], v[48:51], off offset:64
	v_max_f32_e32 v44, v44, v44
	v_max_f32_e32 v45, v45, v45
	v_pk_mul_f32 v[48:49], v[40:41], v[40:41]
	v_max_f32_e32 v41, v42, v42
	v_max_f32_e32 v40, v46, v46
	v_max_f32_e32 v42, 0, v41
	v_max_f32_e32 v41, v47, v47
	v_max_f32_e32 v43, v43, v43
	v_mfma_f32_16x16x32_bf16 v[36:39], v[74:77], v[130:133], v[36:39]
	v_max_f32_e32 v44, 0, v44
	v_max_f32_e32 v45, 0, v45
	v_max_f32_e32 v40, 0, v40
	v_max_f32_e32 v41, 0, v41
	v_max_f32_e32 v43, 0, v43
	v_pk_mul_f32 v[44:45], v[44:45], v[44:45]
	v_pk_mul_f32 v[46:47], v[40:41], v[40:41]
	v_pk_mul_f32 v[50:51], v[42:43], v[42:43]
	v_max_f32_e32 v32, v32, v32
	v_max_f32_e32 v33, v33, v33
	v_mfma_f32_16x16x32_bf16 v[24:27], v[146:149], v[134:137], v[24:27]
	v_cvt_pk_bf16_f32 v40, v44, v45
	v_cvt_pk_bf16_f32 v41, v46, v47
	v_cvt_pk_bf16_f32 v42, v48, v49
	v_cvt_pk_bf16_f32 v43, v50, v51
	v_max_f32_e32 v32, 0, v32
	v_max_f32_e32 v33, 0, v33
	global_store_dwordx4 v[100:101], v[40:43], off offset:128
	v_max_f32_e32 v36, v36, v36
	v_max_f32_e32 v37, v37, v37
	v_pk_mul_f32 v[40:41], v[32:33], v[32:33]
	v_max_f32_e32 v33, v34, v34
	v_max_f32_e32 v32, v38, v38
	v_max_f32_e32 v34, 0, v33
	v_max_f32_e32 v33, v39, v39
	v_max_f32_e32 v35, v35, v35
	v_mfma_f32_16x16x32_bf16 v[28:31], v[138:141], v[134:137], v[28:31]
	v_max_f32_e32 v36, 0, v36
	v_max_f32_e32 v37, 0, v37
	v_max_f32_e32 v32, 0, v32
	v_max_f32_e32 v33, 0, v33
	v_max_f32_e32 v35, 0, v35
	v_pk_mul_f32 v[36:37], v[36:37], v[36:37]
	v_pk_mul_f32 v[38:39], v[32:33], v[32:33]
	v_pk_mul_f32 v[42:43], v[34:35], v[34:35]
	v_max_f32_e32 v24, v24, v24
	v_max_f32_e32 v25, v25, v25
	v_mfma_f32_16x16x32_bf16 v[12:15], v[150:153], v[134:137], v[12:15]
	v_cvt_pk_bf16_f32 v32, v36, v37
	v_cvt_pk_bf16_f32 v33, v38, v39
	v_cvt_pk_bf16_f32 v34, v40, v41
	v_cvt_pk_bf16_f32 v35, v42, v43
	v_max_f32_e32 v24, 0, v24
	v_max_f32_e32 v25, 0, v25
	global_store_dwordx4 v[100:101], v[32:35], off offset:192
	v_max_f32_e32 v28, v28, v28
	v_max_f32_e32 v29, v29, v29
	v_pk_mul_f32 v[34:35], v[24:25], v[24:25]
	v_max_f32_e32 v25, v26, v26
	v_add_u32_e32 v32, s33, v84
	v_max_f32_e32 v24, v30, v30
	v_max_f32_e32 v26, 0, v25
	v_max_f32_e32 v25, v31, v31
	v_max_f32_e32 v27, v27, v27
	v_mfma_f32_16x16x32_bf16 v[20:23], v[94:97], v[134:137], v[20:23]
	v_mad_i64_i32 v[32:33], s[34:35], v32, s29, v[98:99]
	v_max_f32_e32 v28, 0, v28
	v_max_f32_e32 v29, 0, v29
	v_max_f32_e32 v24, 0, v24
	v_max_f32_e32 v25, 0, v25
	v_max_f32_e32 v27, 0, v27
	v_lshl_add_u64 v[32:33], v[32:33], 0, s[26:27]
	v_pk_mul_f32 v[28:29], v[28:29], v[28:29]
	v_pk_mul_f32 v[30:31], v[24:25], v[24:25]
	v_pk_mul_f32 v[36:37], v[26:27], v[26:27]
	v_max_f32_e32 v12, v12, v12
	v_max_f32_e32 v13, v13, v13
	v_mfma_f32_16x16x32_bf16 v[4:7], v[158:161], v[134:137], v[4:7]
	v_lshl_add_u64 v[32:33], v[32:33], 0, v[64:65]
	v_cvt_pk_bf16_f32 v24, v28, v29
	v_cvt_pk_bf16_f32 v25, v30, v31
	v_cvt_pk_bf16_f32 v26, v34, v35
	v_cvt_pk_bf16_f32 v27, v36, v37
	v_max_f32_e32 v12, 0, v12
	v_max_f32_e32 v13, 0, v13
	global_store_dwordx4 v[32:33], v[24:27], off
	v_max_f32_e32 v20, v20, v20
	v_max_f32_e32 v21, v21, v21
	v_pk_mul_f32 v[24:25], v[12:13], v[12:13]
	v_max_f32_e32 v13, v14, v14
	v_max_f32_e32 v12, v22, v22
	v_max_f32_e32 v14, 0, v13
	v_max_f32_e32 v13, v23, v23
	v_max_f32_e32 v15, v15, v15
	v_mfma_f32_16x16x32_bf16 v[8:11], v[154:157], v[134:137], v[8:11]
	v_max_f32_e32 v20, 0, v20
	v_max_f32_e32 v21, 0, v21
	v_max_f32_e32 v12, 0, v12
	v_max_f32_e32 v13, 0, v13
	v_max_f32_e32 v15, 0, v15
	v_pk_mul_f32 v[20:21], v[20:21], v[20:21]
	v_pk_mul_f32 v[22:23], v[12:13], v[12:13]
	v_pk_mul_f32 v[26:27], v[14:15], v[14:15]
	v_max_f32_e32 v4, v4, v4
	v_max_f32_e32 v5, v5, v5
	v_cvt_pk_bf16_f32 v12, v20, v21
	v_cvt_pk_bf16_f32 v13, v22, v23
	v_cvt_pk_bf16_f32 v14, v24, v25
	v_cvt_pk_bf16_f32 v15, v26, v27
	v_max_f32_e32 v4, 0, v4
	v_max_f32_e32 v5, 0, v5
	global_store_dwordx4 v[32:33], v[12:15], off offset:64
	v_mfma_f32_16x16x32_bf16 v[0:3], v[74:77], v[134:137], v[0:3]
	v_max_f32_e32 v8, v8, v8
	v_pk_mul_f32 v[12:13], v[4:5], v[4:5]
	v_max_f32_e32 v5, v6, v6
	v_mfma_f32_16x16x32_bf16 v[16:19], v[162:165], v[134:137], v[16:19]
	v_max_f32_e32 v9, v9, v9
	v_max_f32_e32 v4, v10, v10
	v_max_f32_e32 v6, 0, v5
	v_max_f32_e32 v5, v11, v11
	v_max_f32_e32 v7, v7, v7
	v_max_f32_e32 v8, 0, v8
	v_max_f32_e32 v9, 0, v9
	v_max_f32_e32 v4, 0, v4
	v_max_f32_e32 v5, 0, v5
	v_max_f32_e32 v7, 0, v7
	v_pk_mul_f32 v[8:9], v[8:9], v[8:9]
	v_pk_mul_f32 v[10:11], v[4:5], v[4:5]
	v_pk_mul_f32 v[14:15], v[6:7], v[6:7]
	v_cvt_pk_bf16_f32 v4, v8, v9
	v_cvt_pk_bf16_f32 v5, v10, v11
	v_cvt_pk_bf16_f32 v6, v12, v13
	v_cvt_pk_bf16_f32 v7, v14, v15
	global_store_dwordx4 v[32:33], v[4:7], off offset:128
	v_max_f32_e32 v0, v0, v0
	v_max_f32_e32 v1, v1, v1
	v_max_f32_e32 v4, v16, v16
	v_max_f32_e32 v5, v17, v17
	v_max_f32_e32 v2, v2, v2
	v_max_f32_e32 v6, v18, v18
	v_max_f32_e32 v3, v3, v3
	v_max_f32_e32 v7, v19, v19
	v_max_f32_e32 v0, 0, v0
	v_max_f32_e32 v4, 0, v4
	v_max_f32_e32 v1, 0, v1
	v_max_f32_e32 v5, 0, v5
	v_max_f32_e32 v2, 0, v2
	v_max_f32_e32 v6, 0, v6
	v_max_f32_e32 v3, 0, v3
	v_max_f32_e32 v7, 0, v7
	v_pk_mul_f32 v[0:1], v[0:1], v[0:1]
	v_pk_mul_f32 v[4:5], v[4:5], v[4:5]
	v_pk_mul_f32 v[2:3], v[2:3], v[2:3]
	v_pk_mul_f32 v[6:7], v[6:7], v[6:7]
	v_cvt_pk_bf16_f32 v0, v0, v1
	v_cvt_pk_bf16_f32 v1, v2, v3
	v_cvt_pk_bf16_f32 v2, v4, v5
	v_cvt_pk_bf16_f32 v3, v6, v7
	global_store_dwordx4 v[32:33], v[0:3], off offset:192
	s_cbranch_scc0 .LBB0_1754

.LBB0_1824:
	s_add_i32 s41, s39, 0x8000
	s_and_b32 s40, s41, 0x8000
	s_add_i32 s40, s40, 0
	s_add_u32 s86, s40, s87
	s_mov_b32 m0, s86
	s_waitcnt vmcnt(0) lgkmcnt(0)
	s_barrier
	global_load_lds_dwordx4 v244, s[96:97]
	s_add_u32 m0, s86, 0x1000
	s_nop 0
	global_load_lds_dwordx4 v246, s[96:97]
	s_add_u32 m0, s86, 0x2000
	s_nop 0
	global_load_lds_dwordx4 v248, s[96:97]
	s_add_u32 m0, s86, 0x3000
	s_nop 0
	global_load_lds_dwordx4 v250, s[96:97]
	s_add_u32 m0, s86, 0x4000
	s_nop 0
	global_load_lds_dwordx4 v245, s[88:89]
	s_add_u32 m0, s86, 0x5000
	s_nop 0
	global_load_lds_dwordx4 v247, s[88:89]
	s_add_u32 m0, s86, 0x6000
	s_nop 0
	global_load_lds_dwordx4 v249, s[88:89]
	s_add_u32 m0, s86, 0x7000
	s_nop 0
	global_load_lds_dwordx4 v251, s[88:89]
	s_add_u32 s96, s96, 0x80
	s_addc_u32 s97, s97, 0
	s_add_u32 s88, s88, 0x80
	s_addc_u32 s89, s89, 0
	s_and_b32 s39, s39, 0x8000
	s_add_i32 s39, s39, 0
	v_add3_u32 v145, s39, v84, v85
	v_add3_u32 v178, s39, v85, v86
	v_add3_u32 v179, s39, v84, v87
	v_add3_u32 v180, s39, v86, v87
	ds_read_b128 v[104:107], v178
	ds_read_b128 v[76:79], v145 offset:16384
	ds_read_b128 v[100:103], v145 offset:18432
	ds_read_b128 v[108:111], v178 offset:2048
	ds_read_b128 v[112:115], v145 offset:20480
	ds_read_b128 v[116:119], v145 offset:22528
	ds_read_b128 v[120:123], v145 offset:24576
	ds_read_b128 v[124:127], v145 offset:26624
	ds_read_b128 v[128:131], v145 offset:28672
	ds_read_b128 v[132:135], v145 offset:30720
	ds_read_b128 v[146:149], v180
	ds_read_b128 v[136:139], v179 offset:16384
	ds_read_b128 v[140:143], v179 offset:18432
	ds_read_b128 v[150:153], v180 offset:2048
	ds_read_b128 v[154:157], v179 offset:20480
	ds_read_b128 v[158:161], v179 offset:22528
	ds_read_b128 v[162:165], v179 offset:24576
	ds_read_b128 v[166:169], v179 offset:26624
	ds_read_b128 v[170:173], v179 offset:28672
	ds_read_b128 v[174:177], v179 offset:30720
	s_add_u32 s28, s28, 0x80
	s_addc_u32 s29, s29, 0
	s_cmpk_eq_i32 s28, 0x1f80
	s_mov_b32 s39, s41
	s_waitcnt lgkmcnt(15)
	v_mfma_f32_16x16x32_bf16 v[60:63], v[76:79], v[104:107], v[60:63]
	v_mfma_f32_16x16x32_bf16 v[56:59], v[100:103], v[104:107], v[56:59]
	v_mfma_f32_16x16x32_bf16 v[24:27], v[76:79], v[108:111], v[24:27]
	v_mfma_f32_16x16x32_bf16 v[20:23], v[100:103], v[108:111], v[20:23]
	v_mfma_f32_16x16x32_bf16 v[52:55], v[112:115], v[104:107], v[52:55]
	v_mfma_f32_16x16x32_bf16 v[16:19], v[112:115], v[108:111], v[16:19]
	s_waitcnt lgkmcnt(14)
	v_mfma_f32_16x16x32_bf16 v[48:51], v[116:119], v[104:107], v[48:51]
	v_mfma_f32_16x16x32_bf16 v[12:15], v[116:119], v[108:111], v[12:15]
	s_waitcnt lgkmcnt(13)
	v_mfma_f32_16x16x32_bf16 v[44:47], v[120:123], v[104:107], v[44:47]
	v_mfma_f32_16x16x32_bf16 v[8:11], v[120:123], v[108:111], v[8:11]
	s_waitcnt lgkmcnt(12)
	v_mfma_f32_16x16x32_bf16 v[40:43], v[124:127], v[104:107], v[40:43]
	v_mfma_f32_16x16x32_bf16 v[4:7], v[124:127], v[108:111], v[4:7]
	s_waitcnt lgkmcnt(11)
	v_mfma_f32_16x16x32_bf16 v[32:35], v[128:131], v[104:107], v[32:35]
	v_mfma_f32_16x16x32_bf16 v[0:3], v[128:131], v[108:111], v[0:3]
	s_waitcnt lgkmcnt(10)
	v_mfma_f32_16x16x32_bf16 v[28:31], v[132:135], v[104:107], v[28:31]
	v_mfma_f32_16x16x32_bf16 v[36:39], v[132:135], v[108:111], v[36:39]
	s_waitcnt lgkmcnt(8)
	v_mfma_f32_16x16x32_bf16 v[60:63], v[136:139], v[146:149], v[60:63]
	s_waitcnt lgkmcnt(7)
	v_mfma_f32_16x16x32_bf16 v[56:59], v[140:143], v[146:149], v[56:59]
	s_waitcnt lgkmcnt(6)
	v_mfma_f32_16x16x32_bf16 v[24:27], v[136:139], v[150:153], v[24:27]
	v_mfma_f32_16x16x32_bf16 v[20:23], v[140:143], v[150:153], v[20:23]
	s_waitcnt lgkmcnt(5)
	v_mfma_f32_16x16x32_bf16 v[52:55], v[154:157], v[146:149], v[52:55]
	v_mfma_f32_16x16x32_bf16 v[16:19], v[154:157], v[150:153], v[16:19]
	s_waitcnt lgkmcnt(4)
	v_mfma_f32_16x16x32_bf16 v[48:51], v[158:161], v[146:149], v[48:51]
	v_mfma_f32_16x16x32_bf16 v[12:15], v[158:161], v[150:153], v[12:15]
	s_waitcnt lgkmcnt(3)
	v_mfma_f32_16x16x32_bf16 v[44:47], v[162:165], v[146:149], v[44:47]
	v_mfma_f32_16x16x32_bf16 v[8:11], v[162:165], v[150:153], v[8:11]
	s_waitcnt lgkmcnt(2)
	v_mfma_f32_16x16x32_bf16 v[40:43], v[166:169], v[146:149], v[40:43]
	v_mfma_f32_16x16x32_bf16 v[4:7], v[166:169], v[150:153], v[4:7]
	s_waitcnt lgkmcnt(1)
	v_mfma_f32_16x16x32_bf16 v[32:35], v[170:173], v[146:149], v[32:35]
	v_mfma_f32_16x16x32_bf16 v[0:3], v[170:173], v[150:153], v[0:3]
	s_waitcnt lgkmcnt(0)
	v_mfma_f32_16x16x32_bf16 v[28:31], v[174:177], v[146:149], v[28:31]
	v_mfma_f32_16x16x32_bf16 v[36:39], v[174:177], v[150:153], v[36:39]
	s_cbranch_scc0 .LBB0_1824
	v_add_u32_e32 v80, s40, v84
	v_add_u32_e32 v81, v80, v85
	s_waitcnt vmcnt(0)
	s_barrier
	ds_read_b128 v[72:75], v81 offset:16384
	v_add3_u32 v99, s40, v85, v86
	ds_read_b128 v[76:79], v81 offset:18432
	ds_read_b128 v[100:103], v99
	ds_read_b128 v[104:107], v99 offset:2048
	ds_read_b128 v[108:111], v81 offset:20480
	ds_read_b128 v[112:115], v81 offset:22528
	ds_read_b128 v[116:119], v81 offset:24576
	ds_read_b128 v[120:123], v81 offset:26624
	ds_read_b128 v[124:127], v81 offset:28672
	ds_read_b128 v[128:131], v81 offset:30720
	v_add_u32_e32 v80, v80, v87
	s_waitcnt lgkmcnt(7)
	v_mfma_f32_16x16x32_bf16 v[60:63], v[72:75], v[100:103], v[60:63]
	s_lshl_b32 s38, s38, 7
	v_mfma_f32_16x16x32_bf16 v[56:59], v[76:79], v[100:103], v[56:59]
	s_waitcnt lgkmcnt(4)
	v_mfma_f32_16x16x32_bf16 v[48:51], v[112:115], v[100:103], v[48:51]
	s_waitcnt lgkmcnt(3)
	v_mfma_f32_16x16x32_bf16 v[44:47], v[116:119], v[100:103], v[44:47]
	s_waitcnt lgkmcnt(2)
	v_mfma_f32_16x16x32_bf16 v[40:43], v[120:123], v[100:103], v[40:43]
	s_waitcnt lgkmcnt(1)
	v_mfma_f32_16x16x32_bf16 v[32:35], v[124:127], v[100:103], v[32:35]
	s_waitcnt lgkmcnt(0)
	v_mfma_f32_16x16x32_bf16 v[28:31], v[128:131], v[100:103], v[28:31]
	v_mfma_f32_16x16x32_bf16 v[24:27], v[72:75], v[104:107], v[24:27]
	ds_read_b128 v[72:75], v80 offset:16384
	v_mfma_f32_16x16x32_bf16 v[52:55], v[108:111], v[100:103], v[52:55]
	v_mfma_f32_16x16x32_bf16 v[20:23], v[76:79], v[104:107], v[20:23]
	v_mfma_f32_16x16x32_bf16 v[16:19], v[108:111], v[104:107], v[16:19]
	v_mfma_f32_16x16x32_bf16 v[12:15], v[112:115], v[104:107], v[12:15]
	v_mfma_f32_16x16x32_bf16 v[8:11], v[116:119], v[104:107], v[8:11]
	v_mfma_f32_16x16x32_bf16 v[4:7], v[120:123], v[104:107], v[4:7]
	v_mfma_f32_16x16x32_bf16 v[0:3], v[124:127], v[104:107], v[0:3]
	v_mfma_f32_16x16x32_bf16 v[100:103], v[128:131], v[104:107], v[36:39]
	s_nop 2
	v_add3_u32 v36, s40, v87, v86
	ds_read_b128 v[76:79], v80 offset:18432
	ds_read_b128 v[104:107], v36
	ds_read_b128 v[108:111], v36 offset:2048
	ds_read_b128 v[128:131], v80 offset:28672
	ds_read_b128 v[132:135], v80 offset:30720
	ds_read_b128 v[112:115], v80 offset:20480
	ds_read_b128 v[116:119], v80 offset:22528
	ds_read_b128 v[120:123], v80 offset:24576
	ds_read_b128 v[124:127], v80 offset:26624
	s_waitcnt lgkmcnt(7)
	v_mfma_f32_16x16x32_bf16 v[60:63], v[72:75], v[104:107], v[60:63]
	s_waitcnt lgkmcnt(5)
	v_mfma_f32_16x16x32_bf16 v[36:39], v[128:131], v[104:107], v[32:35]
	s_waitcnt lgkmcnt(4)
	v_mfma_f32_16x16x32_bf16 v[32:35], v[132:135], v[104:107], v[28:31]
	v_mfma_f32_16x16x32_bf16 v[28:31], v[72:75], v[108:111], v[24:27]
	v_add_u32_e32 v72, s38, v83
	v_mul_hi_i32 v73, v72, s31
	v_mfma_f32_16x16x32_bf16 v[24:27], v[76:79], v[108:111], v[20:23]
	s_waitcnt lgkmcnt(3)
	v_mfma_f32_16x16x32_bf16 v[20:23], v[112:115], v[108:111], v[16:19]
	s_waitcnt lgkmcnt(2)
	v_mfma_f32_16x16x32_bf16 v[16:19], v[116:119], v[108:111], v[12:15]
	s_waitcnt lgkmcnt(1)
	v_mfma_f32_16x16x32_bf16 v[12:15], v[120:123], v[108:111], v[8:11]
	s_waitcnt lgkmcnt(0)
	v_mfma_f32_16x16x32_bf16 v[8:11], v[124:127], v[108:111], v[4:7]
	s_nop 2
	v_lshrrev_b32_e32 v4, 31, v73
	v_ashrrev_i32_e32 v5, 11, v73
	v_mfma_f32_16x16x32_bf16 v[56:59], v[76:79], v[104:107], v[56:59]
	v_add_u32_e32 v73, v5, v4
	v_mad_i32_i24 v78, v73, s33, v72
	v_lshlrev_b32_e32 v75, 13, v73
	v_mfma_f32_16x16x32_bf16 v[52:55], v[112:115], v[104:107], v[52:55]
	v_cmp_lt_i32_e32 vcc, s34, v78
	v_add3_u32 v74, v75, v78, s35
	v_mfma_f32_16x16x32_bf16 v[48:51], v[116:119], v[104:107], v[48:51]
	v_mfma_f32_16x16x32_bf16 v[44:47], v[120:123], v[104:107], v[44:47]
	v_mfma_f32_16x16x32_bf16 v[40:43], v[124:127], v[104:107], v[40:43]
	v_mfma_f32_16x16x32_bf16 v[4:7], v[128:131], v[108:111], v[0:3]
	v_mfma_f32_16x16x32_bf16 v[0:3], v[132:135], v[108:111], v[100:103]
	s_and_saveexec_b64 s[28:29], vcc
	s_xor_b64 s[28:29], exec, s[28:29]
	v_add3_u32 v72, v75, v78, s35
	s_or_saveexec_b64 s[28:29], s[28:29]
	v_mov_b64_e32 v[76:77], s[92:93]
	v_lshl_add_u32 v75, v73, 8, v78
	s_xor_b64 exec, exec, s[28:29]
	v_lshl_add_u32 v72, v73, 8, v78
	v_mov_b64_e32 v[76:77], s[2:3]
	s_or_b64 exec, exec, s[28:29]
	s_and_saveexec_b64 s[28:29], vcc
	s_xor_b64 s[28:29], exec, s[28:29]
	s_cbranch_execz .LBB0_1831
	v_add_u32_e32 v73, 3, v73
	v_mul_hi_i32_i24_e32 v79, 0x6000, v73
	v_mul_i32_i24_e32 v78, 0x6000, v73
	s_or_saveexec_b64 s[28:29], s[28:29]
	v_mov_b64_e32 v[80:81], s[92:93]
	s_xor_b64 exec, exec, s[28:29]
	s_cbranch_execnz .LBB0_1832
	s_branch .LBB0_1833
